# saddr + both k-steps of each accumulator issued back to back in the GEMM K-loops (D->C forwarding; same per-accumulator order, bit-identical)
# speedup vs baseline: 1.0126x; 1.0033x over previous
.LBB0_109:
	ds_read_b128 v[130:133], v158
	ds_read_b128 v[162:165], v158 offset:1024
	ds_read_b128 v[166:169], v158 offset:2048
	ds_read_b128 v[170:173], v158 offset:3072
	ds_read_b128 v[174:177], v159
	ds_read_b128 v[178:181], v159 offset:1024
	ds_read_b128 v[182:185], v159 offset:2048
	ds_read_b128 v[186:189], v159 offset:3072
	s_add_u32 s22, s20, 0xfff04000
	s_addc_u32 s23, s21, -1
	s_cmp_eq_u32 s46, 60
	s_cselect_b32 s26, s42, s22
	s_cselect_b32 s27, s15, s23
	s_cselect_b32 s24, s43, s44
	s_cselect_b32 s25, s13, s45
	s_add_u32 s22, s26, 0x4000
	s_addc_u32 s23, s27, 0
	s_add_i32 m0, s29, 0xc000
	ds_read_b128 v[190:193], v160
	ds_read_b128 v[194:197], v160 offset:1024
	ds_read_b128 v[198:201], v160 offset:2048
	ds_read_b128 v[202:205], v160 offset:3072
	ds_read_b128 v[206:209], v160 offset:4096
	ds_read_b128 v[210:213], v160 offset:5120
	ds_read_b128 v[214:217], v160 offset:6144
	ds_read_b128 v[218:221], v160 offset:7168
	global_load_lds_dwordx4 v146, s[20:21]
	s_add_i32 m0, s29, 0xe000
	s_nop 0
	global_load_lds_dwordx4 v148, s[20:21]
	s_waitcnt vmcnt(8)
	s_waitcnt lgkmcnt(0)
	s_barrier
	s_setprio 1
	s_waitcnt lgkmcnt(0)
	v_mfma_f32_16x16x32_bf16 v[62:65], v[130:133], v[190:193], v[62:65]
	v_mfma_f32_16x16x32_bf16 v[62:65], v[162:165], v[194:197], v[62:65]
	v_mfma_f32_16x16x32_bf16 v[58:61], v[166:169], v[190:193], v[58:61]
	v_mfma_f32_16x16x32_bf16 v[58:61], v[170:173], v[194:197], v[58:61]
	v_mfma_f32_16x16x32_bf16 v[54:57], v[130:133], v[198:201], v[54:57]
	v_mfma_f32_16x16x32_bf16 v[54:57], v[162:165], v[202:205], v[54:57]
	v_mfma_f32_16x16x32_bf16 v[50:53], v[166:169], v[198:201], v[50:53]
	v_mfma_f32_16x16x32_bf16 v[50:53], v[170:173], v[202:205], v[50:53]
	v_mfma_f32_16x16x32_bf16 v[46:49], v[130:133], v[206:209], v[46:49]
	v_mfma_f32_16x16x32_bf16 v[46:49], v[162:165], v[210:213], v[46:49]
	v_mfma_f32_16x16x32_bf16 v[42:45], v[166:169], v[206:209], v[42:45]
	v_mfma_f32_16x16x32_bf16 v[42:45], v[170:173], v[210:213], v[42:45]
	v_mfma_f32_16x16x32_bf16 v[38:41], v[130:133], v[214:217], v[38:41]
	v_mfma_f32_16x16x32_bf16 v[38:41], v[162:165], v[218:221], v[38:41]
	v_mfma_f32_16x16x32_bf16 v[34:37], v[166:169], v[214:217], v[34:37]
	v_mfma_f32_16x16x32_bf16 v[34:37], v[170:173], v[218:221], v[34:37]
	s_setprio 0
	s_setprio 1
	v_mfma_f32_16x16x32_bf16 v[126:129], v[174:177], v[190:193], v[126:129]
	v_mfma_f32_16x16x32_bf16 v[126:129], v[178:181], v[194:197], v[126:129]
	v_mfma_f32_16x16x32_bf16 v[122:125], v[182:185], v[190:193], v[122:125]
	v_mfma_f32_16x16x32_bf16 v[122:125], v[186:189], v[194:197], v[122:125]
	v_mfma_f32_16x16x32_bf16 v[118:121], v[174:177], v[198:201], v[118:121]
	v_mfma_f32_16x16x32_bf16 v[118:121], v[178:181], v[202:205], v[118:121]
	v_mfma_f32_16x16x32_bf16 v[114:117], v[182:185], v[198:201], v[114:117]
	v_mfma_f32_16x16x32_bf16 v[114:117], v[186:189], v[202:205], v[114:117]
	v_mfma_f32_16x16x32_bf16 v[110:113], v[174:177], v[206:209], v[110:113]
	v_mfma_f32_16x16x32_bf16 v[110:113], v[178:181], v[210:213], v[110:113]
	v_mfma_f32_16x16x32_bf16 v[106:109], v[182:185], v[206:209], v[106:109]
	v_mfma_f32_16x16x32_bf16 v[106:109], v[186:189], v[210:213], v[106:109]
	v_mfma_f32_16x16x32_bf16 v[102:105], v[174:177], v[214:217], v[102:105]
	v_mfma_f32_16x16x32_bf16 v[102:105], v[178:181], v[218:221], v[102:105]
	v_mfma_f32_16x16x32_bf16 v[98:101], v[182:185], v[214:217], v[98:101]
	v_mfma_f32_16x16x32_bf16 v[98:101], v[186:189], v[218:221], v[98:101]
	s_setprio 0
	s_barrier
	s_add_i32 s47, s36, s28
	s_mov_b32 m0, s47
	ds_read_b128 v[190:193], v160 offset:16384
	ds_read_b128 v[194:197], v160 offset:17408
	ds_read_b128 v[198:201], v160 offset:18432
	ds_read_b128 v[202:205], v160 offset:19456
	ds_read_b128 v[206:209], v160 offset:20480
	ds_read_b128 v[210:213], v160 offset:21504
	ds_read_b128 v[214:217], v160 offset:22528
	ds_read_b128 v[218:221], v160 offset:23552
	global_load_lds_dwordx4 v138, s[24:25]
	s_add_i32 m0, s47, 0x2000
	s_add_u32 s48, s24, 0x100000
	s_addc_u32 s49, s25, 0
	s_add_i32 s47, s37, s28
	global_load_lds_dwordx4 v134, s[24:25]
	s_mov_b32 m0, s47
	s_nop 0
	global_load_lds_dwordx4 v138, s[48:49]
	s_add_i32 m0, s47, 0x2000
	s_nop 0
	global_load_lds_dwordx4 v134, s[48:49]
	s_mov_b32 m0, s29
	s_nop 0
	global_load_lds_dwordx4 v140, s[26:27]
	s_mov_b32 m0, s30
	s_nop 0
	global_load_lds_dwordx4 v136, s[26:27]
	s_waitcnt vmcnt(8)
	s_waitcnt lgkmcnt(0)
	s_barrier
	s_setprio 1
	s_waitcnt lgkmcnt(0)
	v_mfma_f32_16x16x32_bf16 v[30:33], v[130:133], v[190:193], v[30:33]
	v_mfma_f32_16x16x32_bf16 v[30:33], v[162:165], v[194:197], v[30:33]
	v_mfma_f32_16x16x32_bf16 v[26:29], v[166:169], v[190:193], v[26:29]
	v_mfma_f32_16x16x32_bf16 v[26:29], v[170:173], v[194:197], v[26:29]
	v_mfma_f32_16x16x32_bf16 v[22:25], v[130:133], v[198:201], v[22:25]
	v_mfma_f32_16x16x32_bf16 v[22:25], v[162:165], v[202:205], v[22:25]
	v_mfma_f32_16x16x32_bf16 v[18:21], v[166:169], v[198:201], v[18:21]
	v_mfma_f32_16x16x32_bf16 v[18:21], v[170:173], v[202:205], v[18:21]
	v_mfma_f32_16x16x32_bf16 v[14:17], v[130:133], v[206:209], v[14:17]
	v_mfma_f32_16x16x32_bf16 v[14:17], v[162:165], v[210:213], v[14:17]
	v_mfma_f32_16x16x32_bf16 v[10:13], v[166:169], v[206:209], v[10:13]
	v_mfma_f32_16x16x32_bf16 v[10:13], v[170:173], v[210:213], v[10:13]
	v_mfma_f32_16x16x32_bf16 v[6:9], v[130:133], v[214:217], v[6:9]
	v_mfma_f32_16x16x32_bf16 v[6:9], v[162:165], v[218:221], v[6:9]
	v_mfma_f32_16x16x32_bf16 v[2:5], v[166:169], v[214:217], v[2:5]
	v_mfma_f32_16x16x32_bf16 v[2:5], v[170:173], v[218:221], v[2:5]
	s_setprio 0
	s_setprio 1
	v_mfma_f32_16x16x32_bf16 v[94:97], v[174:177], v[190:193], v[94:97]
	v_mfma_f32_16x16x32_bf16 v[94:97], v[178:181], v[194:197], v[94:97]
	v_mfma_f32_16x16x32_bf16 v[90:93], v[182:185], v[190:193], v[90:93]
	v_mfma_f32_16x16x32_bf16 v[90:93], v[186:189], v[194:197], v[90:93]
	v_mfma_f32_16x16x32_bf16 v[86:89], v[174:177], v[198:201], v[86:89]
	v_mfma_f32_16x16x32_bf16 v[86:89], v[178:181], v[202:205], v[86:89]
	v_mfma_f32_16x16x32_bf16 v[82:85], v[182:185], v[198:201], v[82:85]
	v_mfma_f32_16x16x32_bf16 v[82:85], v[186:189], v[202:205], v[82:85]
	v_mfma_f32_16x16x32_bf16 v[78:81], v[174:177], v[206:209], v[78:81]
	v_mfma_f32_16x16x32_bf16 v[78:81], v[178:181], v[210:213], v[78:81]
	v_mfma_f32_16x16x32_bf16 v[74:77], v[182:185], v[206:209], v[74:77]
	v_mfma_f32_16x16x32_bf16 v[74:77], v[186:189], v[210:213], v[74:77]
	v_mfma_f32_16x16x32_bf16 v[70:73], v[174:177], v[214:217], v[70:73]
	v_mfma_f32_16x16x32_bf16 v[70:73], v[178:181], v[218:221], v[70:73]
	v_mfma_f32_16x16x32_bf16 v[66:69], v[182:185], v[214:217], v[66:69]
	v_mfma_f32_16x16x32_bf16 v[66:69], v[186:189], v[218:221], v[66:69]
	s_setprio 0
	s_barrier
	s_add_i32 s47, 0, 0x18000
	v_add_u32_e32 v154, s47, v156
	s_add_i32 s48, 0, 0x1c000
	ds_read_b128 v[130:133], v154
	ds_read_b128 v[162:165], v154 offset:1024
	ds_read_b128 v[166:169], v154 offset:2048
	ds_read_b128 v[170:173], v154 offset:3072
	v_add_u32_e32 v154, s48, v156
	ds_read_b128 v[174:177], v154
	ds_read_b128 v[178:181], v154 offset:1024
	ds_read_b128 v[182:185], v154 offset:2048
	ds_read_b128 v[186:189], v154 offset:3072
	s_add_u32 s26, s26, 0x100000
	s_addc_u32 s27, s27, 0
	s_mov_b32 m0, s31
	ds_read_b128 v[190:193], v160 offset:32768
	ds_read_b128 v[194:197], v160 offset:33792
	ds_read_b128 v[198:201], v160 offset:34816
	ds_read_b128 v[202:205], v160 offset:35840
	ds_read_b128 v[206:209], v160 offset:36864
	ds_read_b128 v[210:213], v160 offset:37888
	ds_read_b128 v[214:217], v160 offset:38912
	ds_read_b128 v[218:221], v160 offset:39936
	global_load_lds_dwordx4 v140, s[26:27]
	s_mov_b32 m0, s33
	s_nop 0
	global_load_lds_dwordx4 v136, s[26:27]
	s_waitcnt vmcnt(8)
	s_waitcnt lgkmcnt(0)
	s_barrier
	s_setprio 1
	s_waitcnt lgkmcnt(0)
	v_mfma_f32_16x16x32_bf16 v[62:65], v[130:133], v[190:193], v[62:65]
	v_mfma_f32_16x16x32_bf16 v[62:65], v[162:165], v[194:197], v[62:65]
	v_mfma_f32_16x16x32_bf16 v[58:61], v[166:169], v[190:193], v[58:61]
	v_mfma_f32_16x16x32_bf16 v[58:61], v[170:173], v[194:197], v[58:61]
	v_mfma_f32_16x16x32_bf16 v[54:57], v[130:133], v[198:201], v[54:57]
	v_mfma_f32_16x16x32_bf16 v[54:57], v[162:165], v[202:205], v[54:57]
	v_mfma_f32_16x16x32_bf16 v[50:53], v[166:169], v[198:201], v[50:53]
	v_mfma_f32_16x16x32_bf16 v[50:53], v[170:173], v[202:205], v[50:53]
	v_mfma_f32_16x16x32_bf16 v[46:49], v[130:133], v[206:209], v[46:49]
	v_mfma_f32_16x16x32_bf16 v[46:49], v[162:165], v[210:213], v[46:49]
	v_mfma_f32_16x16x32_bf16 v[42:45], v[166:169], v[206:209], v[42:45]
	v_mfma_f32_16x16x32_bf16 v[42:45], v[170:173], v[210:213], v[42:45]
	v_mfma_f32_16x16x32_bf16 v[38:41], v[130:133], v[214:217], v[38:41]
	v_mfma_f32_16x16x32_bf16 v[38:41], v[162:165], v[218:221], v[38:41]
	v_mfma_f32_16x16x32_bf16 v[34:37], v[166:169], v[214:217], v[34:37]
	v_mfma_f32_16x16x32_bf16 v[34:37], v[170:173], v[218:221], v[34:37]
	s_setprio 0
	s_setprio 1
	v_mfma_f32_16x16x32_bf16 v[126:129], v[174:177], v[190:193], v[126:129]
	v_mfma_f32_16x16x32_bf16 v[126:129], v[178:181], v[194:197], v[126:129]
	v_mfma_f32_16x16x32_bf16 v[122:125], v[182:185], v[190:193], v[122:125]
	v_mfma_f32_16x16x32_bf16 v[122:125], v[186:189], v[194:197], v[122:125]
	v_mfma_f32_16x16x32_bf16 v[118:121], v[174:177], v[198:201], v[118:121]
	v_mfma_f32_16x16x32_bf16 v[118:121], v[178:181], v[202:205], v[118:121]
	v_mfma_f32_16x16x32_bf16 v[114:117], v[182:185], v[198:201], v[114:117]
	v_mfma_f32_16x16x32_bf16 v[114:117], v[186:189], v[202:205], v[114:117]
	v_mfma_f32_16x16x32_bf16 v[110:113], v[174:177], v[206:209], v[110:113]
	v_mfma_f32_16x16x32_bf16 v[110:113], v[178:181], v[210:213], v[110:113]
	v_mfma_f32_16x16x32_bf16 v[106:109], v[182:185], v[206:209], v[106:109]
	v_mfma_f32_16x16x32_bf16 v[106:109], v[186:189], v[210:213], v[106:109]
	v_mfma_f32_16x16x32_bf16 v[102:105], v[174:177], v[214:217], v[102:105]
	v_mfma_f32_16x16x32_bf16 v[102:105], v[178:181], v[218:221], v[102:105]
	v_mfma_f32_16x16x32_bf16 v[98:101], v[182:185], v[214:217], v[98:101]
	v_mfma_f32_16x16x32_bf16 v[98:101], v[186:189], v[218:221], v[98:101]
	s_setprio 0
	s_barrier
	s_add_u32 s26, s24, 0x4000
	s_addc_u32 s27, s25, 0
	s_add_i32 s47, s47, s28
	s_mov_b32 m0, s47
	ds_read_b128 v[190:193], v160 offset:49152
	ds_read_b128 v[194:197], v160 offset:50176
	ds_read_b128 v[198:201], v160 offset:51200
	ds_read_b128 v[202:205], v160 offset:52224
	ds_read_b128 v[206:209], v160 offset:53248
	ds_read_b128 v[210:213], v160 offset:54272
	ds_read_b128 v[214:217], v160 offset:55296
	ds_read_b128 v[218:221], v160 offset:56320
	global_load_lds_dwordx4 v138, s[26:27]
	s_add_i32 m0, s47, 0x2000
	s_add_u32 s24, s24, 0x104000
	s_addc_u32 s25, s25, 0
	global_load_lds_dwordx4 v134, s[26:27]
	s_add_i32 s26, s48, s28
	s_mov_b32 m0, s26
	s_nop 0
	global_load_lds_dwordx4 v138, s[24:25]
	s_add_i32 m0, s26, 0x2000
	s_nop 0
	global_load_lds_dwordx4 v134, s[24:25]
	s_mov_b32 m0, s34
	s_nop 0
	global_load_lds_dwordx4 v140, s[22:23]
	s_mov_b32 m0, s35
	s_nop 0
	global_load_lds_dwordx4 v136, s[22:23]
	s_waitcnt vmcnt(8)
	s_waitcnt lgkmcnt(0)
	s_barrier
	s_setprio 1
	s_waitcnt lgkmcnt(0)
	v_mfma_f32_16x16x32_bf16 v[30:33], v[130:133], v[190:193], v[30:33]
	v_mfma_f32_16x16x32_bf16 v[30:33], v[162:165], v[194:197], v[30:33]
	v_mfma_f32_16x16x32_bf16 v[26:29], v[166:169], v[190:193], v[26:29]
	v_mfma_f32_16x16x32_bf16 v[26:29], v[170:173], v[194:197], v[26:29]
	v_mfma_f32_16x16x32_bf16 v[22:25], v[130:133], v[198:201], v[22:25]
	v_mfma_f32_16x16x32_bf16 v[22:25], v[162:165], v[202:205], v[22:25]
	v_mfma_f32_16x16x32_bf16 v[18:21], v[166:169], v[198:201], v[18:21]
	v_mfma_f32_16x16x32_bf16 v[18:21], v[170:173], v[202:205], v[18:21]
	v_mfma_f32_16x16x32_bf16 v[14:17], v[130:133], v[206:209], v[14:17]
	v_mfma_f32_16x16x32_bf16 v[14:17], v[162:165], v[210:213], v[14:17]
	v_mfma_f32_16x16x32_bf16 v[10:13], v[166:169], v[206:209], v[10:13]
	v_mfma_f32_16x16x32_bf16 v[10:13], v[170:173], v[210:213], v[10:13]
	v_mfma_f32_16x16x32_bf16 v[6:9], v[130:133], v[214:217], v[6:9]
	v_mfma_f32_16x16x32_bf16 v[6:9], v[162:165], v[218:221], v[6:9]
	v_mfma_f32_16x16x32_bf16 v[2:5], v[166:169], v[214:217], v[2:5]
	v_mfma_f32_16x16x32_bf16 v[2:5], v[170:173], v[218:221], v[2:5]
	s_setprio 0
	s_setprio 1
	v_mfma_f32_16x16x32_bf16 v[94:97], v[174:177], v[190:193], v[94:97]
	v_mfma_f32_16x16x32_bf16 v[94:97], v[178:181], v[194:197], v[94:97]
	v_mfma_f32_16x16x32_bf16 v[90:93], v[182:185], v[190:193], v[90:93]
	v_mfma_f32_16x16x32_bf16 v[90:93], v[186:189], v[194:197], v[90:93]
	v_mfma_f32_16x16x32_bf16 v[86:89], v[174:177], v[198:201], v[86:89]
	v_mfma_f32_16x16x32_bf16 v[86:89], v[178:181], v[202:205], v[86:89]
	v_mfma_f32_16x16x32_bf16 v[82:85], v[182:185], v[198:201], v[82:85]
	v_mfma_f32_16x16x32_bf16 v[82:85], v[186:189], v[202:205], v[82:85]
	v_mfma_f32_16x16x32_bf16 v[78:81], v[174:177], v[206:209], v[78:81]
	v_mfma_f32_16x16x32_bf16 v[78:81], v[178:181], v[210:213], v[78:81]
	v_mfma_f32_16x16x32_bf16 v[74:77], v[182:185], v[206:209], v[74:77]
	v_mfma_f32_16x16x32_bf16 v[74:77], v[186:189], v[210:213], v[74:77]
	v_mfma_f32_16x16x32_bf16 v[70:73], v[174:177], v[214:217], v[70:73]
	v_mfma_f32_16x16x32_bf16 v[70:73], v[178:181], v[218:221], v[70:73]
	v_mfma_f32_16x16x32_bf16 v[66:69], v[182:185], v[214:217], v[66:69]
	v_mfma_f32_16x16x32_bf16 v[66:69], v[186:189], v[218:221], v[66:69]
	s_setprio 0
	s_barrier
	s_add_i32 s46, s46, 2
	s_add_u32 s20, s20, 0x8000
	s_addc_u32 s21, s21, 0
	s_add_u32 s44, s44, 0x8000
	s_addc_u32 s45, s45, 0
	s_cmp_gt_u32 s46, 61
	s_cbranch_scc0 .LBB0_109
	s_and_b64 vcc, exec, s[8:9]
	s_cbranch_vccnz .LBB0_113
	v_lshl_add_u32 v154, s4, 8, v1
	s_cmp_lg_u32 s41, 24
	s_mov_b64 s[20:21], -1
	s_cbranch_scc1 .LBB0_114

.LBB0_376:
	ds_read_b128 v[130:133], v159
	ds_read_b128 v[162:165], v159 offset:1024
	ds_read_b128 v[166:169], v159 offset:2048
	ds_read_b128 v[170:173], v159 offset:3072
	ds_read_b128 v[174:177], v160
	ds_read_b128 v[178:181], v160 offset:1024
	ds_read_b128 v[182:185], v160 offset:2048
	ds_read_b128 v[186:189], v160 offset:3072
	s_add_u32 s34, s26, 0xfff04000
	s_addc_u32 s35, s27, -1
	s_cmp_eq_u32 s87, 60
	s_cselect_b32 s38, s80, s34
	s_cselect_b32 s39, s21, s35
	s_cselect_b32 s36, s81, s83
	s_cselect_b32 s37, s19, s86
	s_add_u32 s34, s38, 0x4000
	s_addc_u32 s35, s39, 0
	s_add_i32 m0, s46, 0xc000
	ds_read_b128 v[190:193], v161
	ds_read_b128 v[194:197], v161 offset:1024
	ds_read_b128 v[198:201], v161 offset:2048
	ds_read_b128 v[202:205], v161 offset:3072
	ds_read_b128 v[206:209], v161 offset:4096
	ds_read_b128 v[210:213], v161 offset:5120
	ds_read_b128 v[214:217], v161 offset:6144
	ds_read_b128 v[218:221], v161 offset:7168
	global_load_lds_dwordx4 v146, s[26:27]
	s_add_i32 m0, s46, 0xe000
	s_nop 0
	global_load_lds_dwordx4 v148, s[26:27]
	s_waitcnt vmcnt(8)
	s_waitcnt lgkmcnt(0)
	s_barrier
	s_setprio 1
	s_waitcnt lgkmcnt(0)
	v_mfma_f32_16x16x32_bf16 v[62:65], v[130:133], v[190:193], v[62:65]
	v_mfma_f32_16x16x32_bf16 v[62:65], v[162:165], v[194:197], v[62:65]
	v_mfma_f32_16x16x32_bf16 v[58:61], v[166:169], v[190:193], v[58:61]
	v_mfma_f32_16x16x32_bf16 v[58:61], v[170:173], v[194:197], v[58:61]
	v_mfma_f32_16x16x32_bf16 v[54:57], v[130:133], v[198:201], v[54:57]
	v_mfma_f32_16x16x32_bf16 v[54:57], v[162:165], v[202:205], v[54:57]
	v_mfma_f32_16x16x32_bf16 v[50:53], v[166:169], v[198:201], v[50:53]
	v_mfma_f32_16x16x32_bf16 v[50:53], v[170:173], v[202:205], v[50:53]
	v_mfma_f32_16x16x32_bf16 v[46:49], v[130:133], v[206:209], v[46:49]
	v_mfma_f32_16x16x32_bf16 v[46:49], v[162:165], v[210:213], v[46:49]
	v_mfma_f32_16x16x32_bf16 v[42:45], v[166:169], v[206:209], v[42:45]
	v_mfma_f32_16x16x32_bf16 v[42:45], v[170:173], v[210:213], v[42:45]
	v_mfma_f32_16x16x32_bf16 v[38:41], v[130:133], v[214:217], v[38:41]
	v_mfma_f32_16x16x32_bf16 v[38:41], v[162:165], v[218:221], v[38:41]
	v_mfma_f32_16x16x32_bf16 v[34:37], v[166:169], v[214:217], v[34:37]
	v_mfma_f32_16x16x32_bf16 v[34:37], v[170:173], v[218:221], v[34:37]
	s_setprio 0
	s_setprio 1
	v_mfma_f32_16x16x32_bf16 v[126:129], v[174:177], v[190:193], v[126:129]
	v_mfma_f32_16x16x32_bf16 v[126:129], v[178:181], v[194:197], v[126:129]
	v_mfma_f32_16x16x32_bf16 v[122:125], v[182:185], v[190:193], v[122:125]
	v_mfma_f32_16x16x32_bf16 v[122:125], v[186:189], v[194:197], v[122:125]
	v_mfma_f32_16x16x32_bf16 v[118:121], v[174:177], v[198:201], v[118:121]
	v_mfma_f32_16x16x32_bf16 v[118:121], v[178:181], v[202:205], v[118:121]
	v_mfma_f32_16x16x32_bf16 v[114:117], v[182:185], v[198:201], v[114:117]
	v_mfma_f32_16x16x32_bf16 v[114:117], v[186:189], v[202:205], v[114:117]
	v_mfma_f32_16x16x32_bf16 v[110:113], v[174:177], v[206:209], v[110:113]
	v_mfma_f32_16x16x32_bf16 v[110:113], v[178:181], v[210:213], v[110:113]
	v_mfma_f32_16x16x32_bf16 v[106:109], v[182:185], v[206:209], v[106:109]
	v_mfma_f32_16x16x32_bf16 v[106:109], v[186:189], v[210:213], v[106:109]
	v_mfma_f32_16x16x32_bf16 v[102:105], v[174:177], v[214:217], v[102:105]
	v_mfma_f32_16x16x32_bf16 v[102:105], v[178:181], v[218:221], v[102:105]
	v_mfma_f32_16x16x32_bf16 v[98:101], v[182:185], v[214:217], v[98:101]
	v_mfma_f32_16x16x32_bf16 v[98:101], v[186:189], v[218:221], v[98:101]
	s_setprio 0
	s_barrier
	s_add_i32 s88, s66, s41
	s_mov_b32 m0, s88
	ds_read_b128 v[190:193], v161 offset:16384
	ds_read_b128 v[194:197], v161 offset:17408
	ds_read_b128 v[198:201], v161 offset:18432
	ds_read_b128 v[202:205], v161 offset:19456
	ds_read_b128 v[206:209], v161 offset:20480
	ds_read_b128 v[210:213], v161 offset:21504
	ds_read_b128 v[214:217], v161 offset:22528
	ds_read_b128 v[218:221], v161 offset:23552
	global_load_lds_dwordx4 v138, s[36:37]
	s_add_i32 m0, s88, 0x2000
	s_add_u32 s88, s36, 0x100000
	s_addc_u32 s89, s37, 0
	s_add_i32 vcc_lo, s67, s41
	global_load_lds_dwordx4 v134, s[36:37]
	s_mov_b32 m0, vcc_lo
	s_nop 0
	global_load_lds_dwordx4 v138, s[88:89]
	s_add_i32 m0, vcc_lo, 0x2000
	s_nop 0
	global_load_lds_dwordx4 v134, s[88:89]
	s_mov_b32 m0, s46
	s_nop 0
	global_load_lds_dwordx4 v140, s[38:39]
	s_mov_b32 m0, s47
	s_nop 0
	global_load_lds_dwordx4 v136, s[38:39]
	s_waitcnt vmcnt(8)
	s_waitcnt lgkmcnt(0)
	s_barrier
	s_setprio 1
	s_waitcnt lgkmcnt(0)
	v_mfma_f32_16x16x32_bf16 v[30:33], v[130:133], v[190:193], v[30:33]
	v_mfma_f32_16x16x32_bf16 v[30:33], v[162:165], v[194:197], v[30:33]
	v_mfma_f32_16x16x32_bf16 v[26:29], v[166:169], v[190:193], v[26:29]
	v_mfma_f32_16x16x32_bf16 v[26:29], v[170:173], v[194:197], v[26:29]
	v_mfma_f32_16x16x32_bf16 v[22:25], v[130:133], v[198:201], v[22:25]
	v_mfma_f32_16x16x32_bf16 v[22:25], v[162:165], v[202:205], v[22:25]
	v_mfma_f32_16x16x32_bf16 v[18:21], v[166:169], v[198:201], v[18:21]
	v_mfma_f32_16x16x32_bf16 v[18:21], v[170:173], v[202:205], v[18:21]
	v_mfma_f32_16x16x32_bf16 v[14:17], v[130:133], v[206:209], v[14:17]
	v_mfma_f32_16x16x32_bf16 v[14:17], v[162:165], v[210:213], v[14:17]
	v_mfma_f32_16x16x32_bf16 v[10:13], v[166:169], v[206:209], v[10:13]
	v_mfma_f32_16x16x32_bf16 v[10:13], v[170:173], v[210:213], v[10:13]
	v_mfma_f32_16x16x32_bf16 v[6:9], v[130:133], v[214:217], v[6:9]
	v_mfma_f32_16x16x32_bf16 v[6:9], v[162:165], v[218:221], v[6:9]
	v_mfma_f32_16x16x32_bf16 v[2:5], v[166:169], v[214:217], v[2:5]
	v_mfma_f32_16x16x32_bf16 v[2:5], v[170:173], v[218:221], v[2:5]
	s_setprio 0
	s_setprio 1
	v_mfma_f32_16x16x32_bf16 v[94:97], v[174:177], v[190:193], v[94:97]
	v_mfma_f32_16x16x32_bf16 v[94:97], v[178:181], v[194:197], v[94:97]
	v_mfma_f32_16x16x32_bf16 v[90:93], v[182:185], v[190:193], v[90:93]
	v_mfma_f32_16x16x32_bf16 v[90:93], v[186:189], v[194:197], v[90:93]
	v_mfma_f32_16x16x32_bf16 v[86:89], v[174:177], v[198:201], v[86:89]
	v_mfma_f32_16x16x32_bf16 v[86:89], v[178:181], v[202:205], v[86:89]
	v_mfma_f32_16x16x32_bf16 v[82:85], v[182:185], v[198:201], v[82:85]
	v_mfma_f32_16x16x32_bf16 v[82:85], v[186:189], v[202:205], v[82:85]
	v_mfma_f32_16x16x32_bf16 v[78:81], v[174:177], v[206:209], v[78:81]
	v_mfma_f32_16x16x32_bf16 v[78:81], v[178:181], v[210:213], v[78:81]
	v_mfma_f32_16x16x32_bf16 v[74:77], v[182:185], v[206:209], v[74:77]
	v_mfma_f32_16x16x32_bf16 v[74:77], v[186:189], v[210:213], v[74:77]
	v_mfma_f32_16x16x32_bf16 v[70:73], v[174:177], v[214:217], v[70:73]
	v_mfma_f32_16x16x32_bf16 v[70:73], v[178:181], v[218:221], v[70:73]
	v_mfma_f32_16x16x32_bf16 v[66:69], v[182:185], v[214:217], v[66:69]
	v_mfma_f32_16x16x32_bf16 v[66:69], v[186:189], v[218:221], v[66:69]
	s_setprio 0
	s_barrier
	s_add_i32 s88, 0, 0x18000
	v_add_u32_e32 v154, s88, v157
	s_add_i32 s89, 0, 0x1c000
	ds_read_b128 v[130:133], v154
	ds_read_b128 v[162:165], v154 offset:1024
	ds_read_b128 v[166:169], v154 offset:2048
	ds_read_b128 v[170:173], v154 offset:3072
	v_add_u32_e32 v154, s89, v157
	ds_read_b128 v[174:177], v154
	ds_read_b128 v[178:181], v154 offset:1024
	ds_read_b128 v[182:185], v154 offset:2048
	ds_read_b128 v[186:189], v154 offset:3072
	s_add_u32 s38, s38, 0x100000
	s_addc_u32 s39, s39, 0
	s_mov_b32 m0, s58
	ds_read_b128 v[190:193], v161 offset:32768
	ds_read_b128 v[194:197], v161 offset:33792
	ds_read_b128 v[198:201], v161 offset:34816
	ds_read_b128 v[202:205], v161 offset:35840
	ds_read_b128 v[206:209], v161 offset:36864
	ds_read_b128 v[210:213], v161 offset:37888
	ds_read_b128 v[214:217], v161 offset:38912
	ds_read_b128 v[218:221], v161 offset:39936
	global_load_lds_dwordx4 v140, s[38:39]
	s_mov_b32 m0, s59
	s_nop 0
	global_load_lds_dwordx4 v136, s[38:39]
	s_waitcnt vmcnt(8)
	s_waitcnt lgkmcnt(0)
	s_barrier
	s_setprio 1
	s_waitcnt lgkmcnt(0)
	v_mfma_f32_16x16x32_bf16 v[62:65], v[130:133], v[190:193], v[62:65]
	v_mfma_f32_16x16x32_bf16 v[62:65], v[162:165], v[194:197], v[62:65]
	v_mfma_f32_16x16x32_bf16 v[58:61], v[166:169], v[190:193], v[58:61]
	v_mfma_f32_16x16x32_bf16 v[58:61], v[170:173], v[194:197], v[58:61]
	v_mfma_f32_16x16x32_bf16 v[54:57], v[130:133], v[198:201], v[54:57]
	v_mfma_f32_16x16x32_bf16 v[54:57], v[162:165], v[202:205], v[54:57]
	v_mfma_f32_16x16x32_bf16 v[50:53], v[166:169], v[198:201], v[50:53]
	v_mfma_f32_16x16x32_bf16 v[50:53], v[170:173], v[202:205], v[50:53]
	v_mfma_f32_16x16x32_bf16 v[46:49], v[130:133], v[206:209], v[46:49]
	v_mfma_f32_16x16x32_bf16 v[46:49], v[162:165], v[210:213], v[46:49]
	v_mfma_f32_16x16x32_bf16 v[42:45], v[166:169], v[206:209], v[42:45]
	v_mfma_f32_16x16x32_bf16 v[42:45], v[170:173], v[210:213], v[42:45]
	v_mfma_f32_16x16x32_bf16 v[38:41], v[130:133], v[214:217], v[38:41]
	v_mfma_f32_16x16x32_bf16 v[38:41], v[162:165], v[218:221], v[38:41]
	v_mfma_f32_16x16x32_bf16 v[34:37], v[166:169], v[214:217], v[34:37]
	v_mfma_f32_16x16x32_bf16 v[34:37], v[170:173], v[218:221], v[34:37]
	s_setprio 0
	s_setprio 1
	v_mfma_f32_16x16x32_bf16 v[126:129], v[174:177], v[190:193], v[126:129]
	v_mfma_f32_16x16x32_bf16 v[126:129], v[178:181], v[194:197], v[126:129]
	v_mfma_f32_16x16x32_bf16 v[122:125], v[182:185], v[190:193], v[122:125]
	v_mfma_f32_16x16x32_bf16 v[122:125], v[186:189], v[194:197], v[122:125]
	v_mfma_f32_16x16x32_bf16 v[118:121], v[174:177], v[198:201], v[118:121]
	v_mfma_f32_16x16x32_bf16 v[118:121], v[178:181], v[202:205], v[118:121]
	v_mfma_f32_16x16x32_bf16 v[114:117], v[182:185], v[198:201], v[114:117]
	v_mfma_f32_16x16x32_bf16 v[114:117], v[186:189], v[202:205], v[114:117]
	v_mfma_f32_16x16x32_bf16 v[110:113], v[174:177], v[206:209], v[110:113]
	v_mfma_f32_16x16x32_bf16 v[110:113], v[178:181], v[210:213], v[110:113]
	v_mfma_f32_16x16x32_bf16 v[106:109], v[182:185], v[206:209], v[106:109]
	v_mfma_f32_16x16x32_bf16 v[106:109], v[186:189], v[210:213], v[106:109]
	v_mfma_f32_16x16x32_bf16 v[102:105], v[174:177], v[214:217], v[102:105]
	v_mfma_f32_16x16x32_bf16 v[102:105], v[178:181], v[218:221], v[102:105]
	v_mfma_f32_16x16x32_bf16 v[98:101], v[182:185], v[214:217], v[98:101]
	v_mfma_f32_16x16x32_bf16 v[98:101], v[186:189], v[218:221], v[98:101]
	s_setprio 0
	s_barrier
	s_add_u32 s38, s36, 0x4000
	s_addc_u32 s39, s37, 0
	s_add_i32 s88, s88, s41
	s_mov_b32 m0, s88
	ds_read_b128 v[190:193], v161 offset:49152
	ds_read_b128 v[194:197], v161 offset:50176
	ds_read_b128 v[198:201], v161 offset:51200
	ds_read_b128 v[202:205], v161 offset:52224
	ds_read_b128 v[206:209], v161 offset:53248
	ds_read_b128 v[210:213], v161 offset:54272
	ds_read_b128 v[214:217], v161 offset:55296
	ds_read_b128 v[218:221], v161 offset:56320
	global_load_lds_dwordx4 v138, s[38:39]
	s_add_i32 m0, s88, 0x2000
	s_add_u32 s36, s36, 0x104000
	s_addc_u32 s37, s37, 0
	global_load_lds_dwordx4 v134, s[38:39]
	s_add_i32 s38, s89, s41
	s_mov_b32 m0, s38
	s_nop 0
	global_load_lds_dwordx4 v138, s[36:37]
	s_add_i32 m0, s38, 0x2000
	s_nop 0
	global_load_lds_dwordx4 v134, s[36:37]
	s_mov_b32 m0, s64
	s_nop 0
	global_load_lds_dwordx4 v140, s[34:35]
	s_mov_b32 m0, s65
	s_nop 0
	global_load_lds_dwordx4 v136, s[34:35]
	s_waitcnt vmcnt(8)
	s_waitcnt lgkmcnt(0)
	s_barrier
	s_setprio 1
	s_waitcnt lgkmcnt(0)
	v_mfma_f32_16x16x32_bf16 v[30:33], v[130:133], v[190:193], v[30:33]
	v_mfma_f32_16x16x32_bf16 v[30:33], v[162:165], v[194:197], v[30:33]
	v_mfma_f32_16x16x32_bf16 v[26:29], v[166:169], v[190:193], v[26:29]
	v_mfma_f32_16x16x32_bf16 v[26:29], v[170:173], v[194:197], v[26:29]
	v_mfma_f32_16x16x32_bf16 v[22:25], v[130:133], v[198:201], v[22:25]
	v_mfma_f32_16x16x32_bf16 v[22:25], v[162:165], v[202:205], v[22:25]
	v_mfma_f32_16x16x32_bf16 v[18:21], v[166:169], v[198:201], v[18:21]
	v_mfma_f32_16x16x32_bf16 v[18:21], v[170:173], v[202:205], v[18:21]
	v_mfma_f32_16x16x32_bf16 v[14:17], v[130:133], v[206:209], v[14:17]
	v_mfma_f32_16x16x32_bf16 v[14:17], v[162:165], v[210:213], v[14:17]
	v_mfma_f32_16x16x32_bf16 v[10:13], v[166:169], v[206:209], v[10:13]
	v_mfma_f32_16x16x32_bf16 v[10:13], v[170:173], v[210:213], v[10:13]
	v_mfma_f32_16x16x32_bf16 v[6:9], v[130:133], v[214:217], v[6:9]
	v_mfma_f32_16x16x32_bf16 v[6:9], v[162:165], v[218:221], v[6:9]
	v_mfma_f32_16x16x32_bf16 v[2:5], v[166:169], v[214:217], v[2:5]
	v_mfma_f32_16x16x32_bf16 v[2:5], v[170:173], v[218:221], v[2:5]
	s_setprio 0
	s_setprio 1
	v_mfma_f32_16x16x32_bf16 v[94:97], v[174:177], v[190:193], v[94:97]
	v_mfma_f32_16x16x32_bf16 v[94:97], v[178:181], v[194:197], v[94:97]
	v_mfma_f32_16x16x32_bf16 v[90:93], v[182:185], v[190:193], v[90:93]
	v_mfma_f32_16x16x32_bf16 v[90:93], v[186:189], v[194:197], v[90:93]
	v_mfma_f32_16x16x32_bf16 v[86:89], v[174:177], v[198:201], v[86:89]
	v_mfma_f32_16x16x32_bf16 v[86:89], v[178:181], v[202:205], v[86:89]
	v_mfma_f32_16x16x32_bf16 v[82:85], v[182:185], v[198:201], v[82:85]
	v_mfma_f32_16x16x32_bf16 v[82:85], v[186:189], v[202:205], v[82:85]
	v_mfma_f32_16x16x32_bf16 v[78:81], v[174:177], v[206:209], v[78:81]
	v_mfma_f32_16x16x32_bf16 v[78:81], v[178:181], v[210:213], v[78:81]
	v_mfma_f32_16x16x32_bf16 v[74:77], v[182:185], v[206:209], v[74:77]
	v_mfma_f32_16x16x32_bf16 v[74:77], v[186:189], v[210:213], v[74:77]
	v_mfma_f32_16x16x32_bf16 v[70:73], v[174:177], v[214:217], v[70:73]
	v_mfma_f32_16x16x32_bf16 v[70:73], v[178:181], v[218:221], v[70:73]
	v_mfma_f32_16x16x32_bf16 v[66:69], v[182:185], v[214:217], v[66:69]
	v_mfma_f32_16x16x32_bf16 v[66:69], v[186:189], v[218:221], v[66:69]
	s_setprio 0
	s_barrier
	s_add_i32 s87, s87, 2
	s_add_u32 s26, s26, 0x8000
	s_addc_u32 s27, s27, 0
	s_add_u32 s83, s83, 0x8000
	s_addc_u32 s86, s86, 0
	s_cmp_gt_u32 s87, 61
	s_cbranch_scc0 .LBB0_376
	s_and_b64 vcc, exec, s[14:15]
	s_cbranch_vccz .LBB0_379
	s_barrier

.LBB0_536:
	ds_read_b128 v[130:133], v159
	ds_read_b128 v[162:165], v159 offset:1024
	ds_read_b128 v[166:169], v159 offset:2048
	ds_read_b128 v[170:173], v159 offset:3072
	ds_read_b128 v[174:177], v160
	ds_read_b128 v[178:181], v160 offset:1024
	ds_read_b128 v[182:185], v160 offset:2048
	ds_read_b128 v[186:189], v160 offset:3072
	s_add_u32 s30, s26, 0xfff04000
	s_addc_u32 s31, s27, -1
	s_cmp_eq_u32 s80, 60
	s_cselect_b32 s36, s74, s30
	s_cselect_b32 s37, s21, s31
	s_cselect_b32 s34, s75, s78
	s_cselect_b32 s35, s19, s79
	s_add_u32 s30, s36, 0x4000
	s_addc_u32 s31, s37, 0
	s_add_i32 m0, s42, 0xc000
	ds_read_b128 v[190:193], v161
	ds_read_b128 v[194:197], v161 offset:1024
	ds_read_b128 v[198:201], v161 offset:2048
	ds_read_b128 v[202:205], v161 offset:3072
	ds_read_b128 v[206:209], v161 offset:4096
	ds_read_b128 v[210:213], v161 offset:5120
	ds_read_b128 v[214:217], v161 offset:6144
	ds_read_b128 v[218:221], v161 offset:7168
	global_load_lds_dwordx4 v146, s[26:27]
	s_add_i32 m0, s42, 0xe000
	s_nop 0
	global_load_lds_dwordx4 v148, s[26:27]
	s_waitcnt vmcnt(8)
	s_waitcnt lgkmcnt(0)
	s_barrier
	s_setprio 1
	s_waitcnt lgkmcnt(0)
	v_mfma_f32_16x16x32_bf16 v[62:65], v[130:133], v[190:193], v[62:65]
	v_mfma_f32_16x16x32_bf16 v[62:65], v[162:165], v[194:197], v[62:65]
	v_mfma_f32_16x16x32_bf16 v[58:61], v[166:169], v[190:193], v[58:61]
	v_mfma_f32_16x16x32_bf16 v[58:61], v[170:173], v[194:197], v[58:61]
	v_mfma_f32_16x16x32_bf16 v[54:57], v[130:133], v[198:201], v[54:57]
	v_mfma_f32_16x16x32_bf16 v[54:57], v[162:165], v[202:205], v[54:57]
	v_mfma_f32_16x16x32_bf16 v[50:53], v[166:169], v[198:201], v[50:53]
	v_mfma_f32_16x16x32_bf16 v[50:53], v[170:173], v[202:205], v[50:53]
	v_mfma_f32_16x16x32_bf16 v[46:49], v[130:133], v[206:209], v[46:49]
	v_mfma_f32_16x16x32_bf16 v[46:49], v[162:165], v[210:213], v[46:49]
	v_mfma_f32_16x16x32_bf16 v[42:45], v[166:169], v[206:209], v[42:45]
	v_mfma_f32_16x16x32_bf16 v[42:45], v[170:173], v[210:213], v[42:45]
	v_mfma_f32_16x16x32_bf16 v[38:41], v[130:133], v[214:217], v[38:41]
	v_mfma_f32_16x16x32_bf16 v[38:41], v[162:165], v[218:221], v[38:41]
	v_mfma_f32_16x16x32_bf16 v[34:37], v[166:169], v[214:217], v[34:37]
	v_mfma_f32_16x16x32_bf16 v[34:37], v[170:173], v[218:221], v[34:37]
	s_setprio 0
	s_setprio 1
	v_mfma_f32_16x16x32_bf16 v[126:129], v[174:177], v[190:193], v[126:129]
	v_mfma_f32_16x16x32_bf16 v[126:129], v[178:181], v[194:197], v[126:129]
	v_mfma_f32_16x16x32_bf16 v[122:125], v[182:185], v[190:193], v[122:125]
	v_mfma_f32_16x16x32_bf16 v[122:125], v[186:189], v[194:197], v[122:125]
	v_mfma_f32_16x16x32_bf16 v[118:121], v[174:177], v[198:201], v[118:121]
	v_mfma_f32_16x16x32_bf16 v[118:121], v[178:181], v[202:205], v[118:121]
	v_mfma_f32_16x16x32_bf16 v[114:117], v[182:185], v[198:201], v[114:117]
	v_mfma_f32_16x16x32_bf16 v[114:117], v[186:189], v[202:205], v[114:117]
	v_mfma_f32_16x16x32_bf16 v[110:113], v[174:177], v[206:209], v[110:113]
	v_mfma_f32_16x16x32_bf16 v[110:113], v[178:181], v[210:213], v[110:113]
	v_mfma_f32_16x16x32_bf16 v[106:109], v[182:185], v[206:209], v[106:109]
	v_mfma_f32_16x16x32_bf16 v[106:109], v[186:189], v[210:213], v[106:109]
	v_mfma_f32_16x16x32_bf16 v[102:105], v[174:177], v[214:217], v[102:105]
	v_mfma_f32_16x16x32_bf16 v[102:105], v[178:181], v[218:221], v[102:105]
	v_mfma_f32_16x16x32_bf16 v[98:101], v[182:185], v[214:217], v[98:101]
	v_mfma_f32_16x16x32_bf16 v[98:101], v[186:189], v[218:221], v[98:101]
	s_setprio 0
	s_barrier
	s_add_i32 s81, s62, s38
	s_mov_b32 m0, s81
	ds_read_b128 v[190:193], v161 offset:16384
	ds_read_b128 v[194:197], v161 offset:17408
	ds_read_b128 v[198:201], v161 offset:18432
	ds_read_b128 v[202:205], v161 offset:19456
	ds_read_b128 v[206:209], v161 offset:20480
	ds_read_b128 v[210:213], v161 offset:21504
	ds_read_b128 v[214:217], v161 offset:22528
	ds_read_b128 v[218:221], v161 offset:23552
	global_load_lds_dwordx4 v138, s[34:35]
	s_add_i32 m0, s81, 0x2000
	s_add_u32 s86, s34, 0x100000
	s_addc_u32 s87, s35, 0
	s_add_i32 s81, s63, s38
	global_load_lds_dwordx4 v134, s[34:35]
	s_mov_b32 m0, s81
	s_nop 0
	global_load_lds_dwordx4 v138, s[86:87]
	s_add_i32 m0, s81, 0x2000
	s_nop 0
	global_load_lds_dwordx4 v134, s[86:87]
	s_mov_b32 m0, s42
	s_nop 0
	global_load_lds_dwordx4 v140, s[36:37]
	s_mov_b32 m0, s43
	s_nop 0
	global_load_lds_dwordx4 v136, s[36:37]
	s_waitcnt vmcnt(8)
	s_waitcnt lgkmcnt(0)
	s_barrier
	s_setprio 1
	s_waitcnt lgkmcnt(0)
	v_mfma_f32_16x16x32_bf16 v[30:33], v[130:133], v[190:193], v[30:33]
	v_mfma_f32_16x16x32_bf16 v[30:33], v[162:165], v[194:197], v[30:33]
	v_mfma_f32_16x16x32_bf16 v[26:29], v[166:169], v[190:193], v[26:29]
	v_mfma_f32_16x16x32_bf16 v[26:29], v[170:173], v[194:197], v[26:29]
	v_mfma_f32_16x16x32_bf16 v[22:25], v[130:133], v[198:201], v[22:25]
	v_mfma_f32_16x16x32_bf16 v[22:25], v[162:165], v[202:205], v[22:25]
	v_mfma_f32_16x16x32_bf16 v[18:21], v[166:169], v[198:201], v[18:21]
	v_mfma_f32_16x16x32_bf16 v[18:21], v[170:173], v[202:205], v[18:21]
	v_mfma_f32_16x16x32_bf16 v[14:17], v[130:133], v[206:209], v[14:17]
	v_mfma_f32_16x16x32_bf16 v[14:17], v[162:165], v[210:213], v[14:17]
	v_mfma_f32_16x16x32_bf16 v[10:13], v[166:169], v[206:209], v[10:13]
	v_mfma_f32_16x16x32_bf16 v[10:13], v[170:173], v[210:213], v[10:13]
	v_mfma_f32_16x16x32_bf16 v[6:9], v[130:133], v[214:217], v[6:9]
	v_mfma_f32_16x16x32_bf16 v[6:9], v[162:165], v[218:221], v[6:9]
	v_mfma_f32_16x16x32_bf16 v[2:5], v[166:169], v[214:217], v[2:5]
	v_mfma_f32_16x16x32_bf16 v[2:5], v[170:173], v[218:221], v[2:5]
	s_setprio 0
	s_setprio 1
	v_mfma_f32_16x16x32_bf16 v[94:97], v[174:177], v[190:193], v[94:97]
	v_mfma_f32_16x16x32_bf16 v[94:97], v[178:181], v[194:197], v[94:97]
	v_mfma_f32_16x16x32_bf16 v[90:93], v[182:185], v[190:193], v[90:93]
	v_mfma_f32_16x16x32_bf16 v[90:93], v[186:189], v[194:197], v[90:93]
	v_mfma_f32_16x16x32_bf16 v[86:89], v[174:177], v[198:201], v[86:89]
	v_mfma_f32_16x16x32_bf16 v[86:89], v[178:181], v[202:205], v[86:89]
	v_mfma_f32_16x16x32_bf16 v[82:85], v[182:185], v[198:201], v[82:85]
	v_mfma_f32_16x16x32_bf16 v[82:85], v[186:189], v[202:205], v[82:85]
	v_mfma_f32_16x16x32_bf16 v[78:81], v[174:177], v[206:209], v[78:81]
	v_mfma_f32_16x16x32_bf16 v[78:81], v[178:181], v[210:213], v[78:81]
	v_mfma_f32_16x16x32_bf16 v[74:77], v[182:185], v[206:209], v[74:77]
	v_mfma_f32_16x16x32_bf16 v[74:77], v[186:189], v[210:213], v[74:77]
	v_mfma_f32_16x16x32_bf16 v[70:73], v[174:177], v[214:217], v[70:73]
	v_mfma_f32_16x16x32_bf16 v[70:73], v[178:181], v[218:221], v[70:73]
	v_mfma_f32_16x16x32_bf16 v[66:69], v[182:185], v[214:217], v[66:69]
	v_mfma_f32_16x16x32_bf16 v[66:69], v[186:189], v[218:221], v[66:69]
	s_setprio 0
	s_barrier
	s_add_i32 s81, 0, 0x18000
	v_add_u32_e32 v154, s81, v157
	s_add_i32 s83, 0, 0x1c000
	ds_read_b128 v[130:133], v154
	ds_read_b128 v[162:165], v154 offset:1024
	ds_read_b128 v[166:169], v154 offset:2048
	ds_read_b128 v[170:173], v154 offset:3072
	v_add_u32_e32 v154, s83, v157
	ds_read_b128 v[174:177], v154
	ds_read_b128 v[178:181], v154 offset:1024
	ds_read_b128 v[182:185], v154 offset:2048
	ds_read_b128 v[186:189], v154 offset:3072
	s_add_u32 s36, s36, 0x100000
	s_addc_u32 s37, s37, 0
	s_mov_b32 m0, s46
	ds_read_b128 v[190:193], v161 offset:32768
	ds_read_b128 v[194:197], v161 offset:33792
	ds_read_b128 v[198:201], v161 offset:34816
	ds_read_b128 v[202:205], v161 offset:35840
	ds_read_b128 v[206:209], v161 offset:36864
	ds_read_b128 v[210:213], v161 offset:37888
	ds_read_b128 v[214:217], v161 offset:38912
	ds_read_b128 v[218:221], v161 offset:39936
	global_load_lds_dwordx4 v140, s[36:37]
	s_mov_b32 m0, s47
	s_nop 0
	global_load_lds_dwordx4 v136, s[36:37]
	s_waitcnt vmcnt(8)
	s_waitcnt lgkmcnt(0)
	s_barrier
	s_setprio 1
	s_waitcnt lgkmcnt(0)
	v_mfma_f32_16x16x32_bf16 v[62:65], v[130:133], v[190:193], v[62:65]
	v_mfma_f32_16x16x32_bf16 v[62:65], v[162:165], v[194:197], v[62:65]
	v_mfma_f32_16x16x32_bf16 v[58:61], v[166:169], v[190:193], v[58:61]
	v_mfma_f32_16x16x32_bf16 v[58:61], v[170:173], v[194:197], v[58:61]
	v_mfma_f32_16x16x32_bf16 v[54:57], v[130:133], v[198:201], v[54:57]
	v_mfma_f32_16x16x32_bf16 v[54:57], v[162:165], v[202:205], v[54:57]
	v_mfma_f32_16x16x32_bf16 v[50:53], v[166:169], v[198:201], v[50:53]
	v_mfma_f32_16x16x32_bf16 v[50:53], v[170:173], v[202:205], v[50:53]
	v_mfma_f32_16x16x32_bf16 v[46:49], v[130:133], v[206:209], v[46:49]
	v_mfma_f32_16x16x32_bf16 v[46:49], v[162:165], v[210:213], v[46:49]
	v_mfma_f32_16x16x32_bf16 v[42:45], v[166:169], v[206:209], v[42:45]
	v_mfma_f32_16x16x32_bf16 v[42:45], v[170:173], v[210:213], v[42:45]
	v_mfma_f32_16x16x32_bf16 v[38:41], v[130:133], v[214:217], v[38:41]
	v_mfma_f32_16x16x32_bf16 v[38:41], v[162:165], v[218:221], v[38:41]
	v_mfma_f32_16x16x32_bf16 v[34:37], v[166:169], v[214:217], v[34:37]
	v_mfma_f32_16x16x32_bf16 v[34:37], v[170:173], v[218:221], v[34:37]
	s_setprio 0
	s_setprio 1
	v_mfma_f32_16x16x32_bf16 v[126:129], v[174:177], v[190:193], v[126:129]
	v_mfma_f32_16x16x32_bf16 v[126:129], v[178:181], v[194:197], v[126:129]
	v_mfma_f32_16x16x32_bf16 v[122:125], v[182:185], v[190:193], v[122:125]
	v_mfma_f32_16x16x32_bf16 v[122:125], v[186:189], v[194:197], v[122:125]
	v_mfma_f32_16x16x32_bf16 v[118:121], v[174:177], v[198:201], v[118:121]
	v_mfma_f32_16x16x32_bf16 v[118:121], v[178:181], v[202:205], v[118:121]
	v_mfma_f32_16x16x32_bf16 v[114:117], v[182:185], v[198:201], v[114:117]
	v_mfma_f32_16x16x32_bf16 v[114:117], v[186:189], v[202:205], v[114:117]
	v_mfma_f32_16x16x32_bf16 v[110:113], v[174:177], v[206:209], v[110:113]
	v_mfma_f32_16x16x32_bf16 v[110:113], v[178:181], v[210:213], v[110:113]
	v_mfma_f32_16x16x32_bf16 v[106:109], v[182:185], v[206:209], v[106:109]
	v_mfma_f32_16x16x32_bf16 v[106:109], v[186:189], v[210:213], v[106:109]
	v_mfma_f32_16x16x32_bf16 v[102:105], v[174:177], v[214:217], v[102:105]
	v_mfma_f32_16x16x32_bf16 v[102:105], v[178:181], v[218:221], v[102:105]
	v_mfma_f32_16x16x32_bf16 v[98:101], v[182:185], v[214:217], v[98:101]
	v_mfma_f32_16x16x32_bf16 v[98:101], v[186:189], v[218:221], v[98:101]
	s_setprio 0
	s_barrier
	s_add_u32 s36, s34, 0x4000
	s_addc_u32 s37, s35, 0
	s_add_i32 s81, s81, s38
	s_mov_b32 m0, s81
	ds_read_b128 v[190:193], v161 offset:49152
	ds_read_b128 v[194:197], v161 offset:50176
	ds_read_b128 v[198:201], v161 offset:51200
	ds_read_b128 v[202:205], v161 offset:52224
	ds_read_b128 v[206:209], v161 offset:53248
	ds_read_b128 v[210:213], v161 offset:54272
	ds_read_b128 v[214:217], v161 offset:55296
	ds_read_b128 v[218:221], v161 offset:56320
	global_load_lds_dwordx4 v138, s[36:37]
	s_add_i32 m0, s81, 0x2000
	s_add_u32 s34, s34, 0x104000
	s_addc_u32 s35, s35, 0
	global_load_lds_dwordx4 v134, s[36:37]
	s_add_i32 s36, s83, s38
	s_mov_b32 m0, s36
	s_nop 0
	global_load_lds_dwordx4 v138, s[34:35]
	s_add_i32 m0, s36, 0x2000
	s_nop 0
	global_load_lds_dwordx4 v134, s[34:35]
	s_mov_b32 m0, s58
	s_nop 0
	global_load_lds_dwordx4 v140, s[30:31]
	s_mov_b32 m0, s59
	s_nop 0
	global_load_lds_dwordx4 v136, s[30:31]
	s_waitcnt vmcnt(8)
	s_waitcnt lgkmcnt(0)
	s_barrier
	s_setprio 1
	s_waitcnt lgkmcnt(0)
	v_mfma_f32_16x16x32_bf16 v[30:33], v[130:133], v[190:193], v[30:33]
	v_mfma_f32_16x16x32_bf16 v[30:33], v[162:165], v[194:197], v[30:33]
	v_mfma_f32_16x16x32_bf16 v[26:29], v[166:169], v[190:193], v[26:29]
	v_mfma_f32_16x16x32_bf16 v[26:29], v[170:173], v[194:197], v[26:29]
	v_mfma_f32_16x16x32_bf16 v[22:25], v[130:133], v[198:201], v[22:25]
	v_mfma_f32_16x16x32_bf16 v[22:25], v[162:165], v[202:205], v[22:25]
	v_mfma_f32_16x16x32_bf16 v[18:21], v[166:169], v[198:201], v[18:21]
	v_mfma_f32_16x16x32_bf16 v[18:21], v[170:173], v[202:205], v[18:21]
	v_mfma_f32_16x16x32_bf16 v[14:17], v[130:133], v[206:209], v[14:17]
	v_mfma_f32_16x16x32_bf16 v[14:17], v[162:165], v[210:213], v[14:17]
	v_mfma_f32_16x16x32_bf16 v[10:13], v[166:169], v[206:209], v[10:13]
	v_mfma_f32_16x16x32_bf16 v[10:13], v[170:173], v[210:213], v[10:13]
	v_mfma_f32_16x16x32_bf16 v[6:9], v[130:133], v[214:217], v[6:9]
	v_mfma_f32_16x16x32_bf16 v[6:9], v[162:165], v[218:221], v[6:9]
	v_mfma_f32_16x16x32_bf16 v[2:5], v[166:169], v[214:217], v[2:5]
	v_mfma_f32_16x16x32_bf16 v[2:5], v[170:173], v[218:221], v[2:5]
	s_setprio 0
	s_setprio 1
	v_mfma_f32_16x16x32_bf16 v[94:97], v[174:177], v[190:193], v[94:97]
	v_mfma_f32_16x16x32_bf16 v[94:97], v[178:181], v[194:197], v[94:97]
	v_mfma_f32_16x16x32_bf16 v[90:93], v[182:185], v[190:193], v[90:93]
	v_mfma_f32_16x16x32_bf16 v[90:93], v[186:189], v[194:197], v[90:93]
	v_mfma_f32_16x16x32_bf16 v[86:89], v[174:177], v[198:201], v[86:89]
	v_mfma_f32_16x16x32_bf16 v[86:89], v[178:181], v[202:205], v[86:89]
	v_mfma_f32_16x16x32_bf16 v[82:85], v[182:185], v[198:201], v[82:85]
	v_mfma_f32_16x16x32_bf16 v[82:85], v[186:189], v[202:205], v[82:85]
	v_mfma_f32_16x16x32_bf16 v[78:81], v[174:177], v[206:209], v[78:81]
	v_mfma_f32_16x16x32_bf16 v[78:81], v[178:181], v[210:213], v[78:81]
	v_mfma_f32_16x16x32_bf16 v[74:77], v[182:185], v[206:209], v[74:77]
	v_mfma_f32_16x16x32_bf16 v[74:77], v[186:189], v[210:213], v[74:77]
	v_mfma_f32_16x16x32_bf16 v[70:73], v[174:177], v[214:217], v[70:73]
	v_mfma_f32_16x16x32_bf16 v[70:73], v[178:181], v[218:221], v[70:73]
	v_mfma_f32_16x16x32_bf16 v[66:69], v[182:185], v[214:217], v[66:69]
	v_mfma_f32_16x16x32_bf16 v[66:69], v[186:189], v[218:221], v[66:69]
	s_setprio 0
	s_barrier
	s_add_i32 s80, s80, 2
	s_add_u32 s26, s26, 0x8000
	s_addc_u32 s27, s27, 0
	s_add_u32 s78, s78, 0x8000
	s_addc_u32 s79, s79, 0
	s_cmp_gt_u32 s80, 61
	s_cbranch_scc0 .LBB0_536
	s_and_b64 vcc, exec, s[14:15]
	s_cbranch_vccz .LBB0_539
	s_barrier

.LBB0_1005:
	v_add_u32_e32 v142, s46, v200
	v_add_u32_e32 v158, s47, v200
	ds_read_b128 v[130:133], v142
	ds_read_b128 v[134:137], v142 offset:1024
	ds_read_b128 v[138:141], v142 offset:2048
	ds_read_b128 v[142:145], v142 offset:3072
	ds_read_b128 v[146:149], v158
	ds_read_b128 v[150:153], v158 offset:1024
	ds_read_b128 v[154:157], v158 offset:2048
	ds_read_b128 v[158:161], v158 offset:3072
	s_add_i32 s70, s31, 2
	s_add_u32 s26, s24, 0xfff44000
	s_addc_u32 s27, s25, -1
	s_cmp_eq_u32 s67, s31
	s_cselect_b32 s34, s6, s26
	s_cselect_b32 s35, s7, s27
	s_cselect_b32 s30, s20, s68
	s_cselect_b32 s31, s21, s69
	s_add_u32 s26, s34, 0x4000
	s_addc_u32 s27, s35, 0
	s_add_i32 m0, s37, 0xc000
	ds_read_b128 v[162:165], v201
	ds_read_b128 v[166:169], v201 offset:1024
	ds_read_b128 v[170:173], v201 offset:2048
	ds_read_b128 v[174:177], v201 offset:3072
	ds_read_b128 v[202:205], v201 offset:4096
	ds_read_b128 v[206:209], v201 offset:5120
	ds_read_b128 v[210:213], v201 offset:6144
	ds_read_b128 v[214:217], v201 offset:7168
	global_load_lds_dwordx4 v190, s[24:25]
	s_add_i32 m0, s37, 0xe000
	s_nop 0
	global_load_lds_dwordx4 v192, s[24:25]
	s_waitcnt vmcnt(8)
	s_waitcnt lgkmcnt(0)
	s_barrier
	s_setprio 1
	s_waitcnt lgkmcnt(0)
	v_mfma_f32_16x16x32_bf16 v[126:129], v[130:133], v[162:165], v[126:129]
	v_mfma_f32_16x16x32_bf16 v[126:129], v[134:137], v[166:169], v[126:129]
	v_mfma_f32_16x16x32_bf16 v[122:125], v[138:141], v[162:165], v[122:125]
	v_mfma_f32_16x16x32_bf16 v[122:125], v[142:145], v[166:169], v[122:125]
	v_mfma_f32_16x16x32_bf16 v[118:121], v[130:133], v[170:173], v[118:121]
	v_mfma_f32_16x16x32_bf16 v[118:121], v[134:137], v[174:177], v[118:121]
	v_mfma_f32_16x16x32_bf16 v[114:117], v[138:141], v[170:173], v[114:117]
	v_mfma_f32_16x16x32_bf16 v[114:117], v[142:145], v[174:177], v[114:117]
	v_mfma_f32_16x16x32_bf16 v[110:113], v[130:133], v[202:205], v[110:113]
	v_mfma_f32_16x16x32_bf16 v[110:113], v[134:137], v[206:209], v[110:113]
	v_mfma_f32_16x16x32_bf16 v[106:109], v[138:141], v[202:205], v[106:109]
	v_mfma_f32_16x16x32_bf16 v[106:109], v[142:145], v[206:209], v[106:109]
	v_mfma_f32_16x16x32_bf16 v[102:105], v[130:133], v[210:213], v[102:105]
	v_mfma_f32_16x16x32_bf16 v[102:105], v[134:137], v[214:217], v[102:105]
	v_mfma_f32_16x16x32_bf16 v[98:101], v[138:141], v[210:213], v[98:101]
	v_mfma_f32_16x16x32_bf16 v[98:101], v[142:145], v[214:217], v[98:101]
	s_setprio 0
	s_setprio 1
	v_mfma_f32_16x16x32_bf16 v[94:97], v[146:149], v[162:165], v[94:97]
	v_mfma_f32_16x16x32_bf16 v[94:97], v[150:153], v[166:169], v[94:97]
	v_mfma_f32_16x16x32_bf16 v[90:93], v[154:157], v[162:165], v[90:93]
	v_mfma_f32_16x16x32_bf16 v[90:93], v[158:161], v[166:169], v[90:93]
	v_mfma_f32_16x16x32_bf16 v[86:89], v[146:149], v[170:173], v[86:89]
	v_mfma_f32_16x16x32_bf16 v[86:89], v[150:153], v[174:177], v[86:89]
	v_mfma_f32_16x16x32_bf16 v[82:85], v[154:157], v[170:173], v[82:85]
	v_mfma_f32_16x16x32_bf16 v[82:85], v[158:161], v[174:177], v[82:85]
	v_mfma_f32_16x16x32_bf16 v[78:81], v[146:149], v[202:205], v[78:81]
	v_mfma_f32_16x16x32_bf16 v[78:81], v[150:153], v[206:209], v[78:81]
	v_mfma_f32_16x16x32_bf16 v[74:77], v[154:157], v[202:205], v[74:77]
	v_mfma_f32_16x16x32_bf16 v[74:77], v[158:161], v[206:209], v[74:77]
	v_mfma_f32_16x16x32_bf16 v[66:69], v[146:149], v[210:213], v[66:69]
	v_mfma_f32_16x16x32_bf16 v[66:69], v[150:153], v[214:217], v[66:69]
	v_mfma_f32_16x16x32_bf16 v[58:61], v[154:157], v[210:213], v[58:61]
	v_mfma_f32_16x16x32_bf16 v[58:61], v[158:161], v[214:217], v[58:61]
	s_setprio 0
	s_barrier
	s_add_i32 s71, s46, s36
	s_mov_b32 m0, s71
	ds_read_b128 v[162:165], v201 offset:16384
	ds_read_b128 v[166:169], v201 offset:17408
	ds_read_b128 v[170:173], v201 offset:18432
	ds_read_b128 v[174:177], v201 offset:19456
	ds_read_b128 v[202:205], v201 offset:20480
	ds_read_b128 v[206:209], v201 offset:21504
	ds_read_b128 v[210:213], v201 offset:22528
	ds_read_b128 v[214:217], v201 offset:23552
	global_load_lds_dwordx4 v182, s[30:31]
	s_add_i32 m0, s71, 0x2000
	s_add_u32 s72, s30, 0xc0000
	s_addc_u32 s73, s31, 0
	s_add_i32 s71, s47, s36
	global_load_lds_dwordx4 v178, s[30:31]
	s_mov_b32 m0, s71
	s_nop 0
	global_load_lds_dwordx4 v182, s[72:73]
	s_add_i32 m0, s71, 0x2000
	s_nop 0
	global_load_lds_dwordx4 v178, s[72:73]
	s_mov_b32 m0, s37
	s_nop 0
	global_load_lds_dwordx4 v184, s[34:35]
	s_mov_b32 m0, s38
	s_nop 0
	global_load_lds_dwordx4 v180, s[34:35]
	s_waitcnt vmcnt(8)
	s_waitcnt lgkmcnt(0)
	s_barrier
	s_setprio 1
	s_waitcnt lgkmcnt(0)
	v_mfma_f32_16x16x32_bf16 v[70:73], v[130:133], v[162:165], v[70:73]
	v_mfma_f32_16x16x32_bf16 v[70:73], v[134:137], v[166:169], v[70:73]
	v_mfma_f32_16x16x32_bf16 v[62:65], v[138:141], v[162:165], v[62:65]
	v_mfma_f32_16x16x32_bf16 v[62:65], v[142:145], v[166:169], v[62:65]
	v_mfma_f32_16x16x32_bf16 v[54:57], v[130:133], v[170:173], v[54:57]
	v_mfma_f32_16x16x32_bf16 v[54:57], v[134:137], v[174:177], v[54:57]
	v_mfma_f32_16x16x32_bf16 v[50:53], v[138:141], v[170:173], v[50:53]
	v_mfma_f32_16x16x32_bf16 v[50:53], v[142:145], v[174:177], v[50:53]
	v_mfma_f32_16x16x32_bf16 v[46:49], v[130:133], v[202:205], v[46:49]
	v_mfma_f32_16x16x32_bf16 v[46:49], v[134:137], v[206:209], v[46:49]
	v_mfma_f32_16x16x32_bf16 v[42:45], v[138:141], v[202:205], v[42:45]
	v_mfma_f32_16x16x32_bf16 v[42:45], v[142:145], v[206:209], v[42:45]
	v_mfma_f32_16x16x32_bf16 v[38:41], v[130:133], v[210:213], v[38:41]
	v_mfma_f32_16x16x32_bf16 v[38:41], v[134:137], v[214:217], v[38:41]
	v_mfma_f32_16x16x32_bf16 v[34:37], v[138:141], v[210:213], v[34:37]
	v_mfma_f32_16x16x32_bf16 v[34:37], v[142:145], v[214:217], v[34:37]
	s_setprio 0
	s_setprio 1
	v_mfma_f32_16x16x32_bf16 v[30:33], v[146:149], v[162:165], v[30:33]
	v_mfma_f32_16x16x32_bf16 v[30:33], v[150:153], v[166:169], v[30:33]
	v_mfma_f32_16x16x32_bf16 v[26:29], v[154:157], v[162:165], v[26:29]
	v_mfma_f32_16x16x32_bf16 v[26:29], v[158:161], v[166:169], v[26:29]
	v_mfma_f32_16x16x32_bf16 v[22:25], v[146:149], v[170:173], v[22:25]
	v_mfma_f32_16x16x32_bf16 v[22:25], v[150:153], v[174:177], v[22:25]
	v_mfma_f32_16x16x32_bf16 v[18:21], v[154:157], v[170:173], v[18:21]
	v_mfma_f32_16x16x32_bf16 v[18:21], v[158:161], v[174:177], v[18:21]
	v_mfma_f32_16x16x32_bf16 v[14:17], v[146:149], v[202:205], v[14:17]
	v_mfma_f32_16x16x32_bf16 v[14:17], v[150:153], v[206:209], v[14:17]
	v_mfma_f32_16x16x32_bf16 v[10:13], v[154:157], v[202:205], v[10:13]
	v_mfma_f32_16x16x32_bf16 v[10:13], v[158:161], v[206:209], v[10:13]
	v_mfma_f32_16x16x32_bf16 v[6:9], v[146:149], v[210:213], v[6:9]
	v_mfma_f32_16x16x32_bf16 v[6:9], v[150:153], v[214:217], v[6:9]
	v_mfma_f32_16x16x32_bf16 v[2:5], v[154:157], v[210:213], v[2:5]
	v_mfma_f32_16x16x32_bf16 v[2:5], v[158:161], v[214:217], v[2:5]
	s_setprio 0
	s_barrier
	s_add_i32 s71, 0, 0x18000
	s_add_i32 s72, 0, 0x1c000
	v_add_u32_e32 v142, s71, v200
	v_add_u32_e32 v158, s72, v200
	ds_read_b128 v[130:133], v142
	ds_read_b128 v[134:137], v142 offset:1024
	ds_read_b128 v[138:141], v142 offset:2048
	ds_read_b128 v[142:145], v142 offset:3072
	ds_read_b128 v[146:149], v158
	ds_read_b128 v[150:153], v158 offset:1024
	ds_read_b128 v[154:157], v158 offset:2048
	ds_read_b128 v[158:161], v158 offset:3072
	s_add_u32 s34, s34, 0xc0000
	s_addc_u32 s35, s35, 0
	s_mov_b32 m0, s39
	ds_read_b128 v[162:165], v201 offset:32768
	ds_read_b128 v[166:169], v201 offset:33792
	ds_read_b128 v[170:173], v201 offset:34816
	ds_read_b128 v[174:177], v201 offset:35840
	ds_read_b128 v[202:205], v201 offset:36864
	ds_read_b128 v[206:209], v201 offset:37888
	ds_read_b128 v[210:213], v201 offset:38912
	ds_read_b128 v[214:217], v201 offset:39936
	global_load_lds_dwordx4 v184, s[34:35]
	s_mov_b32 m0, s40
	s_nop 0
	global_load_lds_dwordx4 v180, s[34:35]
	s_waitcnt vmcnt(8)
	s_waitcnt lgkmcnt(0)
	s_barrier
	s_setprio 1
	s_waitcnt lgkmcnt(0)
	v_mfma_f32_16x16x32_bf16 v[126:129], v[130:133], v[162:165], v[126:129]
	v_mfma_f32_16x16x32_bf16 v[126:129], v[134:137], v[166:169], v[126:129]
	v_mfma_f32_16x16x32_bf16 v[122:125], v[138:141], v[162:165], v[122:125]
	v_mfma_f32_16x16x32_bf16 v[122:125], v[142:145], v[166:169], v[122:125]
	v_mfma_f32_16x16x32_bf16 v[118:121], v[130:133], v[170:173], v[118:121]
	v_mfma_f32_16x16x32_bf16 v[118:121], v[134:137], v[174:177], v[118:121]
	v_mfma_f32_16x16x32_bf16 v[114:117], v[138:141], v[170:173], v[114:117]
	v_mfma_f32_16x16x32_bf16 v[114:117], v[142:145], v[174:177], v[114:117]
	v_mfma_f32_16x16x32_bf16 v[110:113], v[130:133], v[202:205], v[110:113]
	v_mfma_f32_16x16x32_bf16 v[110:113], v[134:137], v[206:209], v[110:113]
	v_mfma_f32_16x16x32_bf16 v[106:109], v[138:141], v[202:205], v[106:109]
	v_mfma_f32_16x16x32_bf16 v[106:109], v[142:145], v[206:209], v[106:109]
	v_mfma_f32_16x16x32_bf16 v[102:105], v[130:133], v[210:213], v[102:105]
	v_mfma_f32_16x16x32_bf16 v[102:105], v[134:137], v[214:217], v[102:105]
	v_mfma_f32_16x16x32_bf16 v[98:101], v[138:141], v[210:213], v[98:101]
	v_mfma_f32_16x16x32_bf16 v[98:101], v[142:145], v[214:217], v[98:101]
	s_setprio 0
	s_setprio 1
	v_mfma_f32_16x16x32_bf16 v[94:97], v[146:149], v[162:165], v[94:97]
	v_mfma_f32_16x16x32_bf16 v[94:97], v[150:153], v[166:169], v[94:97]
	v_mfma_f32_16x16x32_bf16 v[90:93], v[154:157], v[162:165], v[90:93]
	v_mfma_f32_16x16x32_bf16 v[90:93], v[158:161], v[166:169], v[90:93]
	v_mfma_f32_16x16x32_bf16 v[86:89], v[146:149], v[170:173], v[86:89]
	v_mfma_f32_16x16x32_bf16 v[86:89], v[150:153], v[174:177], v[86:89]
	v_mfma_f32_16x16x32_bf16 v[82:85], v[154:157], v[170:173], v[82:85]
	v_mfma_f32_16x16x32_bf16 v[82:85], v[158:161], v[174:177], v[82:85]
	v_mfma_f32_16x16x32_bf16 v[78:81], v[146:149], v[202:205], v[78:81]
	v_mfma_f32_16x16x32_bf16 v[78:81], v[150:153], v[206:209], v[78:81]
	v_mfma_f32_16x16x32_bf16 v[74:77], v[154:157], v[202:205], v[74:77]
	v_mfma_f32_16x16x32_bf16 v[74:77], v[158:161], v[206:209], v[74:77]
	v_mfma_f32_16x16x32_bf16 v[66:69], v[146:149], v[210:213], v[66:69]
	v_mfma_f32_16x16x32_bf16 v[66:69], v[150:153], v[214:217], v[66:69]
	v_mfma_f32_16x16x32_bf16 v[58:61], v[154:157], v[210:213], v[58:61]
	v_mfma_f32_16x16x32_bf16 v[58:61], v[158:161], v[214:217], v[58:61]
	s_setprio 0
	s_barrier
	s_add_u32 s34, s30, 0x4000
	s_addc_u32 s35, s31, 0
	s_add_i32 s71, s71, s36
	s_mov_b32 m0, s71
	ds_read_b128 v[162:165], v201 offset:49152
	ds_read_b128 v[166:169], v201 offset:50176
	ds_read_b128 v[170:173], v201 offset:51200
	ds_read_b128 v[174:177], v201 offset:52224
	ds_read_b128 v[202:205], v201 offset:53248
	ds_read_b128 v[206:209], v201 offset:54272
	ds_read_b128 v[210:213], v201 offset:55296
	ds_read_b128 v[214:217], v201 offset:56320
	global_load_lds_dwordx4 v182, s[34:35]
	s_add_i32 m0, s71, 0x2000
	s_add_u32 s30, s30, 0xc4000
	s_addc_u32 s31, s31, 0
	global_load_lds_dwordx4 v178, s[34:35]
	s_add_i32 s34, s72, s36
	s_mov_b32 m0, s34
	s_nop 0
	global_load_lds_dwordx4 v182, s[30:31]
	s_add_i32 m0, s34, 0x2000
	s_nop 0
	global_load_lds_dwordx4 v178, s[30:31]
	s_mov_b32 m0, s42
	s_nop 0
	global_load_lds_dwordx4 v184, s[26:27]
	s_mov_b32 m0, s43
	s_nop 0
	global_load_lds_dwordx4 v180, s[26:27]
	s_waitcnt vmcnt(8)
	s_waitcnt lgkmcnt(0)
	s_barrier
	s_setprio 1
	s_waitcnt lgkmcnt(0)
	v_mfma_f32_16x16x32_bf16 v[70:73], v[130:133], v[162:165], v[70:73]
	v_mfma_f32_16x16x32_bf16 v[70:73], v[134:137], v[166:169], v[70:73]
	v_mfma_f32_16x16x32_bf16 v[62:65], v[138:141], v[162:165], v[62:65]
	v_mfma_f32_16x16x32_bf16 v[62:65], v[142:145], v[166:169], v[62:65]
	v_mfma_f32_16x16x32_bf16 v[54:57], v[130:133], v[170:173], v[54:57]
	v_mfma_f32_16x16x32_bf16 v[54:57], v[134:137], v[174:177], v[54:57]
	v_mfma_f32_16x16x32_bf16 v[50:53], v[138:141], v[170:173], v[50:53]
	v_mfma_f32_16x16x32_bf16 v[50:53], v[142:145], v[174:177], v[50:53]
	v_mfma_f32_16x16x32_bf16 v[46:49], v[130:133], v[202:205], v[46:49]
	v_mfma_f32_16x16x32_bf16 v[46:49], v[134:137], v[206:209], v[46:49]
	v_mfma_f32_16x16x32_bf16 v[42:45], v[138:141], v[202:205], v[42:45]
	v_mfma_f32_16x16x32_bf16 v[42:45], v[142:145], v[206:209], v[42:45]
	v_mfma_f32_16x16x32_bf16 v[38:41], v[130:133], v[210:213], v[38:41]
	v_mfma_f32_16x16x32_bf16 v[38:41], v[134:137], v[214:217], v[38:41]
	v_mfma_f32_16x16x32_bf16 v[34:37], v[138:141], v[210:213], v[34:37]
	v_mfma_f32_16x16x32_bf16 v[34:37], v[142:145], v[214:217], v[34:37]
	s_setprio 0
	s_setprio 1
	v_mfma_f32_16x16x32_bf16 v[30:33], v[146:149], v[162:165], v[30:33]
	v_mfma_f32_16x16x32_bf16 v[30:33], v[150:153], v[166:169], v[30:33]
	v_mfma_f32_16x16x32_bf16 v[26:29], v[154:157], v[162:165], v[26:29]
	v_mfma_f32_16x16x32_bf16 v[26:29], v[158:161], v[166:169], v[26:29]
	v_mfma_f32_16x16x32_bf16 v[22:25], v[146:149], v[170:173], v[22:25]
	v_mfma_f32_16x16x32_bf16 v[22:25], v[150:153], v[174:177], v[22:25]
	v_mfma_f32_16x16x32_bf16 v[18:21], v[154:157], v[170:173], v[18:21]
	v_mfma_f32_16x16x32_bf16 v[18:21], v[158:161], v[174:177], v[18:21]
	v_mfma_f32_16x16x32_bf16 v[14:17], v[146:149], v[202:205], v[14:17]
	v_mfma_f32_16x16x32_bf16 v[14:17], v[150:153], v[206:209], v[14:17]
	v_mfma_f32_16x16x32_bf16 v[10:13], v[154:157], v[202:205], v[10:13]
	v_mfma_f32_16x16x32_bf16 v[10:13], v[158:161], v[206:209], v[10:13]
	v_mfma_f32_16x16x32_bf16 v[6:9], v[146:149], v[210:213], v[6:9]
	v_mfma_f32_16x16x32_bf16 v[6:9], v[150:153], v[214:217], v[6:9]
	v_mfma_f32_16x16x32_bf16 v[2:5], v[154:157], v[210:213], v[2:5]
	v_mfma_f32_16x16x32_bf16 v[2:5], v[158:161], v[214:217], v[2:5]
	s_setprio 0
	s_barrier
	s_add_u32 s24, s24, 0x8000
	s_addc_u32 s25, s25, 0
	s_add_u32 s68, s68, 0x8000
	s_addc_u32 s69, s69, 0
	s_cmp_ge_u32 s70, s66
	s_mov_b32 s31, s70
	s_cbranch_scc0 .LBB0_1005
	s_and_b64 vcc, exec, s[18:19]
	s_cbranch_vccnz .LBB0_1010
	v_lshl_add_u32 v162, s65, 8, v189
	s_mov_b64 s[24:25], -1
	s_and_b64 vcc, exec, s[22:23]
	s_cbranch_vccnz .LBB0_1011

.LBB0_1088:
	ds_read_b128 v[130:133], v209
	ds_read_b128 v[134:137], v209 offset:1024
	ds_read_b128 v[138:141], v209 offset:2048
	ds_read_b128 v[142:145], v209 offset:3072
	ds_read_b128 v[146:149], v210
	ds_read_b128 v[150:153], v210 offset:1024
	ds_read_b128 v[154:157], v210 offset:2048
	ds_read_b128 v[158:161], v210 offset:3072
	s_add_u32 s38, s36, 0xfff04000
	s_addc_u32 s39, s37, -1
	s_cmp_eq_u32 s72, 60
	s_cselect_b32 s42, s35, s38
	s_cselect_b32 s43, s25, s39
	s_cselect_b32 s40, s69, s70
	s_cselect_b32 s41, s23, s71
	s_add_u32 s38, s42, 0x4000
	s_addc_u32 s39, s43, 0
	s_add_i32 m0, s47, 0xc000
	ds_read_b128 v[162:165], v211
	ds_read_b128 v[166:169], v211 offset:1024
	ds_read_b128 v[170:173], v211 offset:2048
	ds_read_b128 v[174:177], v211 offset:3072
	ds_read_b128 v[196:199], v211 offset:4096
	ds_read_b128 v[200:203], v211 offset:5120
	ds_read_b128 v[214:217], v211 offset:6144
	ds_read_b128 v[218:221], v211 offset:7168
	global_load_lds_dwordx4 v188, s[36:37]
	s_add_i32 m0, s47, 0xe000
	s_nop 0
	global_load_lds_dwordx4 v190, s[36:37]
	s_waitcnt vmcnt(8)
	s_waitcnt lgkmcnt(0)
	s_barrier
	s_setprio 1
	s_waitcnt lgkmcnt(0)
	v_mfma_f32_16x16x32_bf16 v[126:129], v[130:133], v[162:165], v[126:129]
	v_mfma_f32_16x16x32_bf16 v[126:129], v[134:137], v[166:169], v[126:129]
	v_mfma_f32_16x16x32_bf16 v[122:125], v[138:141], v[162:165], v[122:125]
	v_mfma_f32_16x16x32_bf16 v[122:125], v[142:145], v[166:169], v[122:125]
	v_mfma_f32_16x16x32_bf16 v[110:113], v[130:133], v[170:173], v[110:113]
	v_mfma_f32_16x16x32_bf16 v[110:113], v[134:137], v[174:177], v[110:113]
	v_mfma_f32_16x16x32_bf16 v[106:109], v[138:141], v[170:173], v[106:109]
	v_mfma_f32_16x16x32_bf16 v[106:109], v[142:145], v[174:177], v[106:109]
	v_mfma_f32_16x16x32_bf16 v[94:97], v[130:133], v[196:199], v[94:97]
	v_mfma_f32_16x16x32_bf16 v[94:97], v[134:137], v[200:203], v[94:97]
	v_mfma_f32_16x16x32_bf16 v[90:93], v[138:141], v[196:199], v[90:93]
	v_mfma_f32_16x16x32_bf16 v[90:93], v[142:145], v[200:203], v[90:93]
	v_mfma_f32_16x16x32_bf16 v[78:81], v[130:133], v[214:217], v[78:81]
	v_mfma_f32_16x16x32_bf16 v[78:81], v[134:137], v[218:221], v[78:81]
	v_mfma_f32_16x16x32_bf16 v[74:77], v[138:141], v[214:217], v[74:77]
	v_mfma_f32_16x16x32_bf16 v[74:77], v[142:145], v[218:221], v[74:77]
	s_setprio 0
	s_setprio 1
	v_mfma_f32_16x16x32_bf16 v[118:121], v[146:149], v[162:165], v[118:121]
	v_mfma_f32_16x16x32_bf16 v[118:121], v[150:153], v[166:169], v[118:121]
	v_mfma_f32_16x16x32_bf16 v[114:117], v[154:157], v[162:165], v[114:117]
	v_mfma_f32_16x16x32_bf16 v[114:117], v[158:161], v[166:169], v[114:117]
	v_mfma_f32_16x16x32_bf16 v[102:105], v[146:149], v[170:173], v[102:105]
	v_mfma_f32_16x16x32_bf16 v[102:105], v[150:153], v[174:177], v[102:105]
	v_mfma_f32_16x16x32_bf16 v[98:101], v[154:157], v[170:173], v[98:101]
	v_mfma_f32_16x16x32_bf16 v[98:101], v[158:161], v[174:177], v[98:101]
	v_mfma_f32_16x16x32_bf16 v[86:89], v[146:149], v[196:199], v[86:89]
	v_mfma_f32_16x16x32_bf16 v[86:89], v[150:153], v[200:203], v[86:89]
	v_mfma_f32_16x16x32_bf16 v[82:85], v[154:157], v[196:199], v[82:85]
	v_mfma_f32_16x16x32_bf16 v[82:85], v[158:161], v[200:203], v[82:85]
	v_mfma_f32_16x16x32_bf16 v[70:73], v[146:149], v[214:217], v[70:73]
	v_mfma_f32_16x16x32_bf16 v[70:73], v[150:153], v[218:221], v[70:73]
	v_mfma_f32_16x16x32_bf16 v[66:69], v[154:157], v[214:217], v[66:69]
	v_mfma_f32_16x16x32_bf16 v[66:69], v[158:161], v[218:221], v[66:69]
	s_setprio 0
	s_barrier
	s_add_i32 s73, s66, s46
	s_mov_b32 m0, s73
	ds_read_b128 v[162:165], v211 offset:16384
	ds_read_b128 v[166:169], v211 offset:17408
	ds_read_b128 v[170:173], v211 offset:18432
	ds_read_b128 v[174:177], v211 offset:19456
	ds_read_b128 v[196:199], v211 offset:20480
	ds_read_b128 v[200:203], v211 offset:21504
	ds_read_b128 v[214:217], v211 offset:22528
	ds_read_b128 v[218:221], v211 offset:23552
	global_load_lds_dwordx4 v180, s[40:41]
	s_add_i32 m0, s73, 0x2000
	s_add_u32 s74, s40, 0x100000
	s_addc_u32 s75, s41, 0
	s_add_i32 s73, s67, s46
	global_load_lds_dwordx4 v184, s[40:41]
	s_mov_b32 m0, s73
	s_nop 0
	global_load_lds_dwordx4 v180, s[74:75]
	s_add_i32 m0, s73, 0x2000
	s_nop 0
	global_load_lds_dwordx4 v184, s[74:75]
	s_mov_b32 m0, s47
	s_nop 0
	global_load_lds_dwordx4 v178, s[42:43]
	s_mov_b32 m0, s59
	s_nop 0
	global_load_lds_dwordx4 v182, s[42:43]
	s_waitcnt vmcnt(8)
	s_waitcnt lgkmcnt(0)
	s_barrier
	s_setprio 1
	s_waitcnt lgkmcnt(0)
	v_mfma_f32_16x16x32_bf16 v[62:65], v[130:133], v[162:165], v[62:65]
	v_mfma_f32_16x16x32_bf16 v[62:65], v[134:137], v[166:169], v[62:65]
	v_mfma_f32_16x16x32_bf16 v[58:61], v[138:141], v[162:165], v[58:61]
	v_mfma_f32_16x16x32_bf16 v[58:61], v[142:145], v[166:169], v[58:61]
	v_mfma_f32_16x16x32_bf16 v[46:49], v[130:133], v[170:173], v[46:49]
	v_mfma_f32_16x16x32_bf16 v[46:49], v[134:137], v[174:177], v[46:49]
	v_mfma_f32_16x16x32_bf16 v[42:45], v[138:141], v[170:173], v[42:45]
	v_mfma_f32_16x16x32_bf16 v[42:45], v[142:145], v[174:177], v[42:45]
	v_mfma_f32_16x16x32_bf16 v[30:33], v[130:133], v[196:199], v[30:33]
	v_mfma_f32_16x16x32_bf16 v[30:33], v[134:137], v[200:203], v[30:33]
	v_mfma_f32_16x16x32_bf16 v[26:29], v[138:141], v[196:199], v[26:29]
	v_mfma_f32_16x16x32_bf16 v[26:29], v[142:145], v[200:203], v[26:29]
	v_mfma_f32_16x16x32_bf16 v[14:17], v[130:133], v[214:217], v[14:17]
	v_mfma_f32_16x16x32_bf16 v[14:17], v[134:137], v[218:221], v[14:17]
	v_mfma_f32_16x16x32_bf16 v[10:13], v[138:141], v[214:217], v[10:13]
	v_mfma_f32_16x16x32_bf16 v[10:13], v[142:145], v[218:221], v[10:13]
	s_setprio 0
	s_setprio 1
	v_mfma_f32_16x16x32_bf16 v[54:57], v[146:149], v[162:165], v[54:57]
	v_mfma_f32_16x16x32_bf16 v[54:57], v[150:153], v[166:169], v[54:57]
	v_mfma_f32_16x16x32_bf16 v[50:53], v[154:157], v[162:165], v[50:53]
	v_mfma_f32_16x16x32_bf16 v[50:53], v[158:161], v[166:169], v[50:53]
	v_mfma_f32_16x16x32_bf16 v[38:41], v[146:149], v[170:173], v[38:41]
	v_mfma_f32_16x16x32_bf16 v[38:41], v[150:153], v[174:177], v[38:41]
	v_mfma_f32_16x16x32_bf16 v[34:37], v[154:157], v[170:173], v[34:37]
	v_mfma_f32_16x16x32_bf16 v[34:37], v[158:161], v[174:177], v[34:37]
	v_mfma_f32_16x16x32_bf16 v[22:25], v[146:149], v[196:199], v[22:25]
	v_mfma_f32_16x16x32_bf16 v[22:25], v[150:153], v[200:203], v[22:25]
	v_mfma_f32_16x16x32_bf16 v[18:21], v[154:157], v[196:199], v[18:21]
	v_mfma_f32_16x16x32_bf16 v[18:21], v[158:161], v[200:203], v[18:21]
	v_mfma_f32_16x16x32_bf16 v[6:9], v[146:149], v[214:217], v[6:9]
	v_mfma_f32_16x16x32_bf16 v[6:9], v[150:153], v[218:221], v[6:9]
	v_mfma_f32_16x16x32_bf16 v[2:5], v[154:157], v[214:217], v[2:5]
	v_mfma_f32_16x16x32_bf16 v[2:5], v[158:161], v[218:221], v[2:5]
	s_setprio 0
	s_barrier
	s_add_i32 s73, 0, 0x18000
	s_add_i32 s74, 0, 0x1c000
	v_add_u32_e32 v142, s73, v208
	v_add_u32_e32 v158, s74, v208
	ds_read_b128 v[130:133], v142
	ds_read_b128 v[134:137], v142 offset:1024
	ds_read_b128 v[138:141], v142 offset:2048
	ds_read_b128 v[142:145], v142 offset:3072
	ds_read_b128 v[146:149], v158
	ds_read_b128 v[150:153], v158 offset:1024
	ds_read_b128 v[154:157], v158 offset:2048
	ds_read_b128 v[158:161], v158 offset:3072
	s_add_u32 s42, s42, 0x100000
	s_addc_u32 s43, s43, 0
	s_mov_b32 m0, s60
	ds_read_b128 v[162:165], v211 offset:32768
	ds_read_b128 v[166:169], v211 offset:33792
	ds_read_b128 v[170:173], v211 offset:34816
	ds_read_b128 v[174:177], v211 offset:35840
	ds_read_b128 v[196:199], v211 offset:36864
	ds_read_b128 v[200:203], v211 offset:37888
	ds_read_b128 v[214:217], v211 offset:38912
	ds_read_b128 v[218:221], v211 offset:39936
	global_load_lds_dwordx4 v178, s[42:43]
	s_mov_b32 m0, s61
	s_nop 0
	global_load_lds_dwordx4 v182, s[42:43]
	s_waitcnt vmcnt(8)
	s_waitcnt lgkmcnt(0)
	s_barrier
	s_setprio 1
	s_waitcnt lgkmcnt(0)
	v_mfma_f32_16x16x32_bf16 v[126:129], v[130:133], v[162:165], v[126:129]
	v_mfma_f32_16x16x32_bf16 v[126:129], v[134:137], v[166:169], v[126:129]
	v_mfma_f32_16x16x32_bf16 v[122:125], v[138:141], v[162:165], v[122:125]
	v_mfma_f32_16x16x32_bf16 v[122:125], v[142:145], v[166:169], v[122:125]
	v_mfma_f32_16x16x32_bf16 v[110:113], v[130:133], v[170:173], v[110:113]
	v_mfma_f32_16x16x32_bf16 v[110:113], v[134:137], v[174:177], v[110:113]
	v_mfma_f32_16x16x32_bf16 v[106:109], v[138:141], v[170:173], v[106:109]
	v_mfma_f32_16x16x32_bf16 v[106:109], v[142:145], v[174:177], v[106:109]
	v_mfma_f32_16x16x32_bf16 v[94:97], v[130:133], v[196:199], v[94:97]
	v_mfma_f32_16x16x32_bf16 v[94:97], v[134:137], v[200:203], v[94:97]
	v_mfma_f32_16x16x32_bf16 v[90:93], v[138:141], v[196:199], v[90:93]
	v_mfma_f32_16x16x32_bf16 v[90:93], v[142:145], v[200:203], v[90:93]
	v_mfma_f32_16x16x32_bf16 v[78:81], v[130:133], v[214:217], v[78:81]
	v_mfma_f32_16x16x32_bf16 v[78:81], v[134:137], v[218:221], v[78:81]
	v_mfma_f32_16x16x32_bf16 v[74:77], v[138:141], v[214:217], v[74:77]
	v_mfma_f32_16x16x32_bf16 v[74:77], v[142:145], v[218:221], v[74:77]
	s_setprio 0
	s_setprio 1
	v_mfma_f32_16x16x32_bf16 v[118:121], v[146:149], v[162:165], v[118:121]
	v_mfma_f32_16x16x32_bf16 v[118:121], v[150:153], v[166:169], v[118:121]
	v_mfma_f32_16x16x32_bf16 v[114:117], v[154:157], v[162:165], v[114:117]
	v_mfma_f32_16x16x32_bf16 v[114:117], v[158:161], v[166:169], v[114:117]
	v_mfma_f32_16x16x32_bf16 v[102:105], v[146:149], v[170:173], v[102:105]
	v_mfma_f32_16x16x32_bf16 v[102:105], v[150:153], v[174:177], v[102:105]
	v_mfma_f32_16x16x32_bf16 v[98:101], v[154:157], v[170:173], v[98:101]
	v_mfma_f32_16x16x32_bf16 v[98:101], v[158:161], v[174:177], v[98:101]
	v_mfma_f32_16x16x32_bf16 v[86:89], v[146:149], v[196:199], v[86:89]
	v_mfma_f32_16x16x32_bf16 v[86:89], v[150:153], v[200:203], v[86:89]
	v_mfma_f32_16x16x32_bf16 v[82:85], v[154:157], v[196:199], v[82:85]
	v_mfma_f32_16x16x32_bf16 v[82:85], v[158:161], v[200:203], v[82:85]
	v_mfma_f32_16x16x32_bf16 v[70:73], v[146:149], v[214:217], v[70:73]
	v_mfma_f32_16x16x32_bf16 v[70:73], v[150:153], v[218:221], v[70:73]
	v_mfma_f32_16x16x32_bf16 v[66:69], v[154:157], v[214:217], v[66:69]
	v_mfma_f32_16x16x32_bf16 v[66:69], v[158:161], v[218:221], v[66:69]
	s_setprio 0
	s_barrier
	s_add_u32 s42, s40, 0x4000
	s_addc_u32 s43, s41, 0
	s_add_i32 s73, s73, s46
	s_mov_b32 m0, s73
	ds_read_b128 v[162:165], v211 offset:49152
	ds_read_b128 v[166:169], v211 offset:50176
	ds_read_b128 v[170:173], v211 offset:51200
	ds_read_b128 v[174:177], v211 offset:52224
	ds_read_b128 v[196:199], v211 offset:53248
	ds_read_b128 v[200:203], v211 offset:54272
	ds_read_b128 v[214:217], v211 offset:55296
	ds_read_b128 v[218:221], v211 offset:56320
	global_load_lds_dwordx4 v180, s[42:43]
	s_add_i32 m0, s73, 0x2000
	s_add_u32 s40, s40, 0x104000
	s_addc_u32 s41, s41, 0
	global_load_lds_dwordx4 v184, s[42:43]
	s_add_i32 s42, s74, s46
	s_mov_b32 m0, s42
	s_nop 0
	global_load_lds_dwordx4 v180, s[40:41]
	s_add_i32 m0, s42, 0x2000
	s_nop 0
	global_load_lds_dwordx4 v184, s[40:41]
	s_mov_b32 m0, s64
	s_nop 0
	global_load_lds_dwordx4 v178, s[38:39]
	s_mov_b32 m0, s65
	s_nop 0
	global_load_lds_dwordx4 v182, s[38:39]
	s_waitcnt vmcnt(8)
	s_waitcnt lgkmcnt(0)
	s_barrier
	s_setprio 1
	s_waitcnt lgkmcnt(0)
	v_mfma_f32_16x16x32_bf16 v[62:65], v[130:133], v[162:165], v[62:65]
	v_mfma_f32_16x16x32_bf16 v[62:65], v[134:137], v[166:169], v[62:65]
	v_mfma_f32_16x16x32_bf16 v[58:61], v[138:141], v[162:165], v[58:61]
	v_mfma_f32_16x16x32_bf16 v[58:61], v[142:145], v[166:169], v[58:61]
	v_mfma_f32_16x16x32_bf16 v[46:49], v[130:133], v[170:173], v[46:49]
	v_mfma_f32_16x16x32_bf16 v[46:49], v[134:137], v[174:177], v[46:49]
	v_mfma_f32_16x16x32_bf16 v[42:45], v[138:141], v[170:173], v[42:45]
	v_mfma_f32_16x16x32_bf16 v[42:45], v[142:145], v[174:177], v[42:45]
	v_mfma_f32_16x16x32_bf16 v[30:33], v[130:133], v[196:199], v[30:33]
	v_mfma_f32_16x16x32_bf16 v[30:33], v[134:137], v[200:203], v[30:33]
	v_mfma_f32_16x16x32_bf16 v[26:29], v[138:141], v[196:199], v[26:29]
	v_mfma_f32_16x16x32_bf16 v[26:29], v[142:145], v[200:203], v[26:29]
	v_mfma_f32_16x16x32_bf16 v[14:17], v[130:133], v[214:217], v[14:17]
	v_mfma_f32_16x16x32_bf16 v[14:17], v[134:137], v[218:221], v[14:17]
	v_mfma_f32_16x16x32_bf16 v[10:13], v[138:141], v[214:217], v[10:13]
	v_mfma_f32_16x16x32_bf16 v[10:13], v[142:145], v[218:221], v[10:13]
	s_setprio 0
	s_setprio 1
	v_mfma_f32_16x16x32_bf16 v[54:57], v[146:149], v[162:165], v[54:57]
	v_mfma_f32_16x16x32_bf16 v[54:57], v[150:153], v[166:169], v[54:57]
	v_mfma_f32_16x16x32_bf16 v[50:53], v[154:157], v[162:165], v[50:53]
	v_mfma_f32_16x16x32_bf16 v[50:53], v[158:161], v[166:169], v[50:53]
	v_mfma_f32_16x16x32_bf16 v[38:41], v[146:149], v[170:173], v[38:41]
	v_mfma_f32_16x16x32_bf16 v[38:41], v[150:153], v[174:177], v[38:41]
	v_mfma_f32_16x16x32_bf16 v[34:37], v[154:157], v[170:173], v[34:37]
	v_mfma_f32_16x16x32_bf16 v[34:37], v[158:161], v[174:177], v[34:37]
	v_mfma_f32_16x16x32_bf16 v[22:25], v[146:149], v[196:199], v[22:25]
	v_mfma_f32_16x16x32_bf16 v[22:25], v[150:153], v[200:203], v[22:25]
	v_mfma_f32_16x16x32_bf16 v[18:21], v[154:157], v[196:199], v[18:21]
	v_mfma_f32_16x16x32_bf16 v[18:21], v[158:161], v[200:203], v[18:21]
	v_mfma_f32_16x16x32_bf16 v[6:9], v[146:149], v[214:217], v[6:9]
	v_mfma_f32_16x16x32_bf16 v[6:9], v[150:153], v[218:221], v[6:9]
	v_mfma_f32_16x16x32_bf16 v[2:5], v[154:157], v[214:217], v[2:5]
	v_mfma_f32_16x16x32_bf16 v[2:5], v[158:161], v[218:221], v[2:5]
	s_setprio 0
	s_barrier
	s_add_i32 s72, s72, 2
	s_add_u32 s36, s36, 0x8000
	s_addc_u32 s37, s37, 0
	s_add_u32 s70, s70, 0x8000
	s_addc_u32 s71, s71, 0
	s_cmp_gt_u32 s72, 61
	s_cbranch_scc0 .LBB0_1088
	s_and_b64 vcc, exec, s[20:21]
	s_cbranch_vccz .LBB0_1091
	s_barrier

.LBB0_1215:
	ds_read_b128 v[160:163], v154
	ds_read_b128 v[164:167], v154 offset:1024
	ds_read_b128 v[168:171], v154 offset:2048
	ds_read_b128 v[172:175], v154 offset:3072
	ds_read_b128 v[176:179], v155
	ds_read_b128 v[180:183], v155 offset:1024
	ds_read_b128 v[184:187], v155 offset:2048
	ds_read_b128 v[188:191], v155 offset:3072
	s_add_u32 s30, s28, 0xfff04000
	s_addc_u32 s31, s29, -1
	s_cmp_eq_u32 s61, 60
	s_cselect_b32 s36, s56, s30
	s_cselect_b32 s37, s21, s31
	s_cselect_b32 s34, s57, s59
	s_cselect_b32 s35, s19, s60
	s_add_u32 s30, s36, 0x4000
	s_addc_u32 s31, s37, 0
	s_add_i32 m0, s39, 0xc000
	ds_read_b128 v[192:195], v156
	ds_read_b128 v[196:199], v156 offset:1024
	ds_read_b128 v[200:203], v156 offset:2048
	ds_read_b128 v[204:207], v156 offset:3072
	ds_read_b128 v[208:211], v156 offset:4096
	ds_read_b128 v[212:215], v156 offset:5120
	ds_read_b128 v[216:219], v156 offset:6144
	ds_read_b128 v[220:223], v156 offset:7168
	global_load_lds_dwordx4 v140, s[28:29]
	s_add_i32 m0, s39, 0xe000
	s_nop 0
	global_load_lds_dwordx4 v142, s[28:29]
	s_waitcnt vmcnt(8)
	s_waitcnt lgkmcnt(0)
	s_barrier
	s_setprio 1
	s_waitcnt lgkmcnt(0)
	v_mfma_f32_16x16x32_bf16 v[126:129], v[160:163], v[192:195], v[126:129]
	v_mfma_f32_16x16x32_bf16 v[126:129], v[164:167], v[196:199], v[126:129]
	v_mfma_f32_16x16x32_bf16 v[122:125], v[168:171], v[192:195], v[122:125]
	v_mfma_f32_16x16x32_bf16 v[122:125], v[172:175], v[196:199], v[122:125]
	v_mfma_f32_16x16x32_bf16 v[110:113], v[160:163], v[200:203], v[110:113]
	v_mfma_f32_16x16x32_bf16 v[110:113], v[164:167], v[204:207], v[110:113]
	v_mfma_f32_16x16x32_bf16 v[106:109], v[168:171], v[200:203], v[106:109]
	v_mfma_f32_16x16x32_bf16 v[106:109], v[172:175], v[204:207], v[106:109]
	v_mfma_f32_16x16x32_bf16 v[94:97], v[160:163], v[208:211], v[94:97]
	v_mfma_f32_16x16x32_bf16 v[94:97], v[164:167], v[212:215], v[94:97]
	v_mfma_f32_16x16x32_bf16 v[90:93], v[168:171], v[208:211], v[90:93]
	v_mfma_f32_16x16x32_bf16 v[90:93], v[172:175], v[212:215], v[90:93]
	v_mfma_f32_16x16x32_bf16 v[78:81], v[160:163], v[216:219], v[78:81]
	v_mfma_f32_16x16x32_bf16 v[78:81], v[164:167], v[220:223], v[78:81]
	v_mfma_f32_16x16x32_bf16 v[74:77], v[168:171], v[216:219], v[74:77]
	v_mfma_f32_16x16x32_bf16 v[74:77], v[172:175], v[220:223], v[74:77]
	s_setprio 0
	s_setprio 1
	v_mfma_f32_16x16x32_bf16 v[118:121], v[176:179], v[192:195], v[118:121]
	v_mfma_f32_16x16x32_bf16 v[118:121], v[180:183], v[196:199], v[118:121]
	v_mfma_f32_16x16x32_bf16 v[114:117], v[184:187], v[192:195], v[114:117]
	v_mfma_f32_16x16x32_bf16 v[114:117], v[188:191], v[196:199], v[114:117]
	v_mfma_f32_16x16x32_bf16 v[102:105], v[176:179], v[200:203], v[102:105]
	v_mfma_f32_16x16x32_bf16 v[102:105], v[180:183], v[204:207], v[102:105]
	v_mfma_f32_16x16x32_bf16 v[98:101], v[184:187], v[200:203], v[98:101]
	v_mfma_f32_16x16x32_bf16 v[98:101], v[188:191], v[204:207], v[98:101]
	v_mfma_f32_16x16x32_bf16 v[86:89], v[176:179], v[208:211], v[86:89]
	v_mfma_f32_16x16x32_bf16 v[86:89], v[180:183], v[212:215], v[86:89]
	v_mfma_f32_16x16x32_bf16 v[82:85], v[184:187], v[208:211], v[82:85]
	v_mfma_f32_16x16x32_bf16 v[82:85], v[188:191], v[212:215], v[82:85]
	v_mfma_f32_16x16x32_bf16 v[70:73], v[176:179], v[216:219], v[70:73]
	v_mfma_f32_16x16x32_bf16 v[70:73], v[180:183], v[220:223], v[70:73]
	v_mfma_f32_16x16x32_bf16 v[66:69], v[184:187], v[216:219], v[66:69]
	v_mfma_f32_16x16x32_bf16 v[66:69], v[188:191], v[220:223], v[66:69]
	s_setprio 0
	s_barrier
	s_add_i32 s62, s47, s38
	s_mov_b32 m0, s62
	ds_read_b128 v[192:195], v156 offset:16384
	ds_read_b128 v[196:199], v156 offset:17408
	ds_read_b128 v[200:203], v156 offset:18432
	ds_read_b128 v[204:207], v156 offset:19456
	ds_read_b128 v[208:211], v156 offset:20480
	ds_read_b128 v[212:215], v156 offset:21504
	ds_read_b128 v[216:219], v156 offset:22528
	ds_read_b128 v[220:223], v156 offset:23552
	global_load_lds_dwordx4 v134, s[34:35]
	s_add_i32 m0, s62, 0x2000
	s_add_u32 s62, s34, 0x100000
	s_addc_u32 s63, s35, 0
	s_add_i32 s64, s54, s38
	global_load_lds_dwordx4 v130, s[34:35]
	s_mov_b32 m0, s64
	s_nop 0
	global_load_lds_dwordx4 v134, s[62:63]
	s_add_i32 m0, s64, 0x2000
	s_nop 0
	global_load_lds_dwordx4 v130, s[62:63]
	s_mov_b32 m0, s39
	s_nop 0
	global_load_lds_dwordx4 v136, s[36:37]
	s_mov_b32 m0, s40
	s_nop 0
	global_load_lds_dwordx4 v132, s[36:37]
	s_waitcnt vmcnt(8)
	s_waitcnt lgkmcnt(0)
	s_barrier
	s_setprio 1
	s_waitcnt lgkmcnt(0)
	v_mfma_f32_16x16x32_bf16 v[62:65], v[160:163], v[192:195], v[62:65]
	v_mfma_f32_16x16x32_bf16 v[62:65], v[164:167], v[196:199], v[62:65]
	v_mfma_f32_16x16x32_bf16 v[58:61], v[168:171], v[192:195], v[58:61]
	v_mfma_f32_16x16x32_bf16 v[58:61], v[172:175], v[196:199], v[58:61]
	v_mfma_f32_16x16x32_bf16 v[46:49], v[160:163], v[200:203], v[46:49]
	v_mfma_f32_16x16x32_bf16 v[46:49], v[164:167], v[204:207], v[46:49]
	v_mfma_f32_16x16x32_bf16 v[42:45], v[168:171], v[200:203], v[42:45]
	v_mfma_f32_16x16x32_bf16 v[42:45], v[172:175], v[204:207], v[42:45]
	v_mfma_f32_16x16x32_bf16 v[30:33], v[160:163], v[208:211], v[30:33]
	v_mfma_f32_16x16x32_bf16 v[30:33], v[164:167], v[212:215], v[30:33]
	v_mfma_f32_16x16x32_bf16 v[26:29], v[168:171], v[208:211], v[26:29]
	v_mfma_f32_16x16x32_bf16 v[26:29], v[172:175], v[212:215], v[26:29]
	v_mfma_f32_16x16x32_bf16 v[14:17], v[160:163], v[216:219], v[14:17]
	v_mfma_f32_16x16x32_bf16 v[14:17], v[164:167], v[220:223], v[14:17]
	v_mfma_f32_16x16x32_bf16 v[10:13], v[168:171], v[216:219], v[10:13]
	v_mfma_f32_16x16x32_bf16 v[10:13], v[172:175], v[220:223], v[10:13]
	s_setprio 0
	s_setprio 1
	v_mfma_f32_16x16x32_bf16 v[54:57], v[176:179], v[192:195], v[54:57]
	v_mfma_f32_16x16x32_bf16 v[54:57], v[180:183], v[196:199], v[54:57]
	v_mfma_f32_16x16x32_bf16 v[50:53], v[184:187], v[192:195], v[50:53]
	v_mfma_f32_16x16x32_bf16 v[50:53], v[188:191], v[196:199], v[50:53]
	v_mfma_f32_16x16x32_bf16 v[38:41], v[176:179], v[200:203], v[38:41]
	v_mfma_f32_16x16x32_bf16 v[38:41], v[180:183], v[204:207], v[38:41]
	v_mfma_f32_16x16x32_bf16 v[34:37], v[184:187], v[200:203], v[34:37]
	v_mfma_f32_16x16x32_bf16 v[34:37], v[188:191], v[204:207], v[34:37]
	v_mfma_f32_16x16x32_bf16 v[22:25], v[176:179], v[208:211], v[22:25]
	v_mfma_f32_16x16x32_bf16 v[22:25], v[180:183], v[212:215], v[22:25]
	v_mfma_f32_16x16x32_bf16 v[18:21], v[184:187], v[208:211], v[18:21]
	v_mfma_f32_16x16x32_bf16 v[18:21], v[188:191], v[212:215], v[18:21]
	v_mfma_f32_16x16x32_bf16 v[6:9], v[176:179], v[216:219], v[6:9]
	v_mfma_f32_16x16x32_bf16 v[6:9], v[180:183], v[220:223], v[6:9]
	v_mfma_f32_16x16x32_bf16 v[2:5], v[184:187], v[216:219], v[2:5]
	v_mfma_f32_16x16x32_bf16 v[2:5], v[188:191], v[220:223], v[2:5]
	s_setprio 0
	s_barrier
	s_add_i32 s62, 0, 0x18000
	v_add_u32_e32 v138, s62, v153
	s_add_i32 s63, 0, 0x1c000
	ds_read_b128 v[160:163], v138
	ds_read_b128 v[164:167], v138 offset:1024
	ds_read_b128 v[168:171], v138 offset:2048
	ds_read_b128 v[172:175], v138 offset:3072
	v_add_u32_e32 v138, s63, v153
	ds_read_b128 v[176:179], v138
	ds_read_b128 v[180:183], v138 offset:1024
	ds_read_b128 v[184:187], v138 offset:2048
	ds_read_b128 v[188:191], v138 offset:3072
	s_add_u32 s36, s36, 0x100000
	s_addc_u32 s37, s37, 0
	s_mov_b32 m0, s41
	ds_read_b128 v[192:195], v156 offset:32768
	ds_read_b128 v[196:199], v156 offset:33792
	ds_read_b128 v[200:203], v156 offset:34816
	ds_read_b128 v[204:207], v156 offset:35840
	ds_read_b128 v[208:211], v156 offset:36864
	ds_read_b128 v[212:215], v156 offset:37888
	ds_read_b128 v[216:219], v156 offset:38912
	ds_read_b128 v[220:223], v156 offset:39936
	global_load_lds_dwordx4 v136, s[36:37]
	s_mov_b32 m0, s42
	s_nop 0
	global_load_lds_dwordx4 v132, s[36:37]
	s_waitcnt vmcnt(8)
	s_waitcnt lgkmcnt(0)
	s_barrier
	s_setprio 1
	s_waitcnt lgkmcnt(0)
	v_mfma_f32_16x16x32_bf16 v[126:129], v[160:163], v[192:195], v[126:129]
	v_mfma_f32_16x16x32_bf16 v[126:129], v[164:167], v[196:199], v[126:129]
	v_mfma_f32_16x16x32_bf16 v[122:125], v[168:171], v[192:195], v[122:125]
	v_mfma_f32_16x16x32_bf16 v[122:125], v[172:175], v[196:199], v[122:125]
	v_mfma_f32_16x16x32_bf16 v[110:113], v[160:163], v[200:203], v[110:113]
	v_mfma_f32_16x16x32_bf16 v[110:113], v[164:167], v[204:207], v[110:113]
	v_mfma_f32_16x16x32_bf16 v[106:109], v[168:171], v[200:203], v[106:109]
	v_mfma_f32_16x16x32_bf16 v[106:109], v[172:175], v[204:207], v[106:109]
	v_mfma_f32_16x16x32_bf16 v[94:97], v[160:163], v[208:211], v[94:97]
	v_mfma_f32_16x16x32_bf16 v[94:97], v[164:167], v[212:215], v[94:97]
	v_mfma_f32_16x16x32_bf16 v[90:93], v[168:171], v[208:211], v[90:93]
	v_mfma_f32_16x16x32_bf16 v[90:93], v[172:175], v[212:215], v[90:93]
	v_mfma_f32_16x16x32_bf16 v[78:81], v[160:163], v[216:219], v[78:81]
	v_mfma_f32_16x16x32_bf16 v[78:81], v[164:167], v[220:223], v[78:81]
	v_mfma_f32_16x16x32_bf16 v[74:77], v[168:171], v[216:219], v[74:77]
	v_mfma_f32_16x16x32_bf16 v[74:77], v[172:175], v[220:223], v[74:77]
	s_setprio 0
	s_setprio 1
	v_mfma_f32_16x16x32_bf16 v[118:121], v[176:179], v[192:195], v[118:121]
	v_mfma_f32_16x16x32_bf16 v[118:121], v[180:183], v[196:199], v[118:121]
	v_mfma_f32_16x16x32_bf16 v[114:117], v[184:187], v[192:195], v[114:117]
	v_mfma_f32_16x16x32_bf16 v[114:117], v[188:191], v[196:199], v[114:117]
	v_mfma_f32_16x16x32_bf16 v[102:105], v[176:179], v[200:203], v[102:105]
	v_mfma_f32_16x16x32_bf16 v[102:105], v[180:183], v[204:207], v[102:105]
	v_mfma_f32_16x16x32_bf16 v[98:101], v[184:187], v[200:203], v[98:101]
	v_mfma_f32_16x16x32_bf16 v[98:101], v[188:191], v[204:207], v[98:101]
	v_mfma_f32_16x16x32_bf16 v[86:89], v[176:179], v[208:211], v[86:89]
	v_mfma_f32_16x16x32_bf16 v[86:89], v[180:183], v[212:215], v[86:89]
	v_mfma_f32_16x16x32_bf16 v[82:85], v[184:187], v[208:211], v[82:85]
	v_mfma_f32_16x16x32_bf16 v[82:85], v[188:191], v[212:215], v[82:85]
	v_mfma_f32_16x16x32_bf16 v[70:73], v[176:179], v[216:219], v[70:73]
	v_mfma_f32_16x16x32_bf16 v[70:73], v[180:183], v[220:223], v[70:73]
	v_mfma_f32_16x16x32_bf16 v[66:69], v[184:187], v[216:219], v[66:69]
	v_mfma_f32_16x16x32_bf16 v[66:69], v[188:191], v[220:223], v[66:69]
	s_setprio 0
	s_barrier
	s_add_u32 s36, s34, 0x4000
	s_addc_u32 s37, s35, 0
	s_add_i32 s62, s62, s38
	s_mov_b32 m0, s62
	ds_read_b128 v[192:195], v156 offset:49152
	ds_read_b128 v[196:199], v156 offset:50176
	ds_read_b128 v[200:203], v156 offset:51200
	ds_read_b128 v[204:207], v156 offset:52224
	ds_read_b128 v[208:211], v156 offset:53248
	ds_read_b128 v[212:215], v156 offset:54272
	ds_read_b128 v[216:219], v156 offset:55296
	ds_read_b128 v[220:223], v156 offset:56320
	global_load_lds_dwordx4 v134, s[36:37]
	s_add_i32 m0, s62, 0x2000
	s_add_u32 s34, s34, 0x104000
	s_addc_u32 s35, s35, 0
	global_load_lds_dwordx4 v130, s[36:37]
	s_add_i32 s36, s63, s38
	s_mov_b32 m0, s36
	s_nop 0
	global_load_lds_dwordx4 v134, s[34:35]
	s_add_i32 m0, s36, 0x2000
	s_nop 0
	global_load_lds_dwordx4 v130, s[34:35]
	s_mov_b32 m0, s45
	s_nop 0
	global_load_lds_dwordx4 v136, s[30:31]
	s_mov_b32 m0, s46
	s_nop 0
	global_load_lds_dwordx4 v132, s[30:31]
	s_waitcnt vmcnt(8)
	s_waitcnt lgkmcnt(0)
	s_barrier
	s_setprio 1
	s_waitcnt lgkmcnt(0)
	v_mfma_f32_16x16x32_bf16 v[62:65], v[160:163], v[192:195], v[62:65]
	v_mfma_f32_16x16x32_bf16 v[62:65], v[164:167], v[196:199], v[62:65]
	v_mfma_f32_16x16x32_bf16 v[58:61], v[168:171], v[192:195], v[58:61]
	v_mfma_f32_16x16x32_bf16 v[58:61], v[172:175], v[196:199], v[58:61]
	v_mfma_f32_16x16x32_bf16 v[46:49], v[160:163], v[200:203], v[46:49]
	v_mfma_f32_16x16x32_bf16 v[46:49], v[164:167], v[204:207], v[46:49]
	v_mfma_f32_16x16x32_bf16 v[42:45], v[168:171], v[200:203], v[42:45]
	v_mfma_f32_16x16x32_bf16 v[42:45], v[172:175], v[204:207], v[42:45]
	v_mfma_f32_16x16x32_bf16 v[30:33], v[160:163], v[208:211], v[30:33]
	v_mfma_f32_16x16x32_bf16 v[30:33], v[164:167], v[212:215], v[30:33]
	v_mfma_f32_16x16x32_bf16 v[26:29], v[168:171], v[208:211], v[26:29]
	v_mfma_f32_16x16x32_bf16 v[26:29], v[172:175], v[212:215], v[26:29]
	v_mfma_f32_16x16x32_bf16 v[14:17], v[160:163], v[216:219], v[14:17]
	v_mfma_f32_16x16x32_bf16 v[14:17], v[164:167], v[220:223], v[14:17]
	v_mfma_f32_16x16x32_bf16 v[10:13], v[168:171], v[216:219], v[10:13]
	v_mfma_f32_16x16x32_bf16 v[10:13], v[172:175], v[220:223], v[10:13]
	s_setprio 0
	s_setprio 1
	v_mfma_f32_16x16x32_bf16 v[54:57], v[176:179], v[192:195], v[54:57]
	v_mfma_f32_16x16x32_bf16 v[54:57], v[180:183], v[196:199], v[54:57]
	v_mfma_f32_16x16x32_bf16 v[50:53], v[184:187], v[192:195], v[50:53]
	v_mfma_f32_16x16x32_bf16 v[50:53], v[188:191], v[196:199], v[50:53]
	v_mfma_f32_16x16x32_bf16 v[38:41], v[176:179], v[200:203], v[38:41]
	v_mfma_f32_16x16x32_bf16 v[38:41], v[180:183], v[204:207], v[38:41]
	v_mfma_f32_16x16x32_bf16 v[34:37], v[184:187], v[200:203], v[34:37]
	v_mfma_f32_16x16x32_bf16 v[34:37], v[188:191], v[204:207], v[34:37]
	v_mfma_f32_16x16x32_bf16 v[22:25], v[176:179], v[208:211], v[22:25]
	v_mfma_f32_16x16x32_bf16 v[22:25], v[180:183], v[212:215], v[22:25]
	v_mfma_f32_16x16x32_bf16 v[18:21], v[184:187], v[208:211], v[18:21]
	v_mfma_f32_16x16x32_bf16 v[18:21], v[188:191], v[212:215], v[18:21]
	v_mfma_f32_16x16x32_bf16 v[6:9], v[176:179], v[216:219], v[6:9]
	v_mfma_f32_16x16x32_bf16 v[6:9], v[180:183], v[220:223], v[6:9]
	v_mfma_f32_16x16x32_bf16 v[2:5], v[184:187], v[216:219], v[2:5]
	v_mfma_f32_16x16x32_bf16 v[2:5], v[188:191], v[220:223], v[2:5]
	s_setprio 0
	s_barrier
	s_add_i32 s61, s61, 2
	s_add_u32 s28, s28, 0x8000
	s_addc_u32 s29, s29, 0
	s_add_u32 s59, s59, 0x8000
	s_addc_u32 s60, s60, 0
	s_cmp_gt_u32 s61, 61
	s_cbranch_scc0 .LBB0_1215
	s_and_b64 vcc, exec, s[16:17]
	s_cbranch_vccz .LBB0_1218
	s_barrier

.LBB0_1292:
	ds_read_b128 v[130:133], v206
	ds_read_b128 v[134:137], v206 offset:1024
	ds_read_b128 v[138:141], v206 offset:2048
	ds_read_b128 v[142:145], v206 offset:3072
	ds_read_b128 v[146:149], v207
	ds_read_b128 v[150:153], v207 offset:1024
	ds_read_b128 v[176:179], v207 offset:2048
	ds_read_b128 v[180:183], v207 offset:3072
	s_add_u32 s42, s40, 0xffc04000
	s_addc_u32 s43, s41, -1
	s_cmpk_eq_i32 s66, 0xfc
	s_cselect_b32 s46, s29, s42
	s_cselect_b32 s47, s14, s43
	s_cselect_b32 s44, s37, s39
	s_cselect_b32 s45, s27, s65
	s_add_u32 s42, s46, 0x4000
	s_addc_u32 s43, s47, 0
	s_add_i32 m0, s53, 0xc000
	ds_read_b128 v[184:187], v208
	ds_read_b128 v[188:191], v208 offset:1024
	ds_read_b128 v[192:195], v208 offset:2048
	ds_read_b128 v[196:199], v208 offset:3072
	ds_read_b128 v[210:213], v208 offset:4096
	ds_read_b128 v[214:217], v208 offset:5120
	ds_read_b128 v[218:221], v208 offset:6144
	ds_read_b128 v[222:225], v208 offset:7168
	global_load_lds_dwordx4 v166, s[40:41]
	s_add_i32 m0, s53, 0xe000
	s_nop 0
	global_load_lds_dwordx4 v168, s[40:41]
	s_waitcnt vmcnt(8)
	s_waitcnt lgkmcnt(0)
	s_barrier
	s_setprio 1
	s_waitcnt lgkmcnt(0)
	v_mfma_f32_16x16x32_bf16 v[126:129], v[130:133], v[184:187], v[126:129]
	v_mfma_f32_16x16x32_bf16 v[126:129], v[134:137], v[188:191], v[126:129]
	v_mfma_f32_16x16x32_bf16 v[122:125], v[138:141], v[184:187], v[122:125]
	v_mfma_f32_16x16x32_bf16 v[122:125], v[142:145], v[188:191], v[122:125]
	v_mfma_f32_16x16x32_bf16 v[110:113], v[130:133], v[192:195], v[110:113]
	v_mfma_f32_16x16x32_bf16 v[110:113], v[134:137], v[196:199], v[110:113]
	v_mfma_f32_16x16x32_bf16 v[106:109], v[138:141], v[192:195], v[106:109]
	v_mfma_f32_16x16x32_bf16 v[106:109], v[142:145], v[196:199], v[106:109]
	v_mfma_f32_16x16x32_bf16 v[94:97], v[130:133], v[210:213], v[94:97]
	v_mfma_f32_16x16x32_bf16 v[94:97], v[134:137], v[214:217], v[94:97]
	v_mfma_f32_16x16x32_bf16 v[90:93], v[138:141], v[210:213], v[90:93]
	v_mfma_f32_16x16x32_bf16 v[90:93], v[142:145], v[214:217], v[90:93]
	v_mfma_f32_16x16x32_bf16 v[78:81], v[130:133], v[218:221], v[78:81]
	v_mfma_f32_16x16x32_bf16 v[78:81], v[134:137], v[222:225], v[78:81]
	v_mfma_f32_16x16x32_bf16 v[74:77], v[138:141], v[218:221], v[74:77]
	v_mfma_f32_16x16x32_bf16 v[74:77], v[142:145], v[222:225], v[74:77]
	s_setprio 0
	s_setprio 1
	v_mfma_f32_16x16x32_bf16 v[118:121], v[146:149], v[184:187], v[118:121]
	v_mfma_f32_16x16x32_bf16 v[118:121], v[150:153], v[188:191], v[118:121]
	v_mfma_f32_16x16x32_bf16 v[114:117], v[176:179], v[184:187], v[114:117]
	v_mfma_f32_16x16x32_bf16 v[114:117], v[180:183], v[188:191], v[114:117]
	v_mfma_f32_16x16x32_bf16 v[102:105], v[146:149], v[192:195], v[102:105]
	v_mfma_f32_16x16x32_bf16 v[102:105], v[150:153], v[196:199], v[102:105]
	v_mfma_f32_16x16x32_bf16 v[98:101], v[176:179], v[192:195], v[98:101]
	v_mfma_f32_16x16x32_bf16 v[98:101], v[180:183], v[196:199], v[98:101]
	v_mfma_f32_16x16x32_bf16 v[86:89], v[146:149], v[210:213], v[86:89]
	v_mfma_f32_16x16x32_bf16 v[86:89], v[150:153], v[214:217], v[86:89]
	v_mfma_f32_16x16x32_bf16 v[82:85], v[176:179], v[210:213], v[82:85]
	v_mfma_f32_16x16x32_bf16 v[82:85], v[180:183], v[214:217], v[82:85]
	v_mfma_f32_16x16x32_bf16 v[70:73], v[146:149], v[218:221], v[70:73]
	v_mfma_f32_16x16x32_bf16 v[70:73], v[150:153], v[222:225], v[70:73]
	v_mfma_f32_16x16x32_bf16 v[66:69], v[176:179], v[218:221], v[66:69]
	v_mfma_f32_16x16x32_bf16 v[66:69], v[180:183], v[222:225], v[66:69]
	s_setprio 0
	s_barrier
	s_add_i32 s67, s62, s52
	s_mov_b32 m0, s67
	ds_read_b128 v[184:187], v208 offset:16384
	ds_read_b128 v[188:191], v208 offset:17408
	ds_read_b128 v[192:195], v208 offset:18432
	ds_read_b128 v[196:199], v208 offset:19456
	ds_read_b128 v[210:213], v208 offset:20480
	ds_read_b128 v[214:217], v208 offset:21504
	ds_read_b128 v[218:221], v208 offset:22528
	ds_read_b128 v[222:225], v208 offset:23552
	global_load_lds_dwordx4 v156, s[44:45]
	s_add_i32 m0, s67, 0x2000
	s_add_u32 s68, s44, 0x400000
	s_addc_u32 s69, s45, 0
	s_add_i32 s67, s63, s52
	global_load_lds_dwordx4 v160, s[44:45]
	s_mov_b32 m0, s67
	s_nop 0
	global_load_lds_dwordx4 v156, s[68:69]
	s_add_i32 m0, s67, 0x2000
	s_nop 0
	global_load_lds_dwordx4 v160, s[68:69]
	s_mov_b32 m0, s53
	s_nop 0
	global_load_lds_dwordx4 v154, s[46:47]
	s_mov_b32 m0, s54
	s_nop 0
	global_load_lds_dwordx4 v158, s[46:47]
	s_waitcnt vmcnt(8)
	s_waitcnt lgkmcnt(0)
	s_barrier
	s_setprio 1
	s_waitcnt lgkmcnt(0)
	v_mfma_f32_16x16x32_bf16 v[62:65], v[130:133], v[184:187], v[62:65]
	v_mfma_f32_16x16x32_bf16 v[62:65], v[134:137], v[188:191], v[62:65]
	v_mfma_f32_16x16x32_bf16 v[58:61], v[138:141], v[184:187], v[58:61]
	v_mfma_f32_16x16x32_bf16 v[58:61], v[142:145], v[188:191], v[58:61]
	v_mfma_f32_16x16x32_bf16 v[46:49], v[130:133], v[192:195], v[46:49]
	v_mfma_f32_16x16x32_bf16 v[46:49], v[134:137], v[196:199], v[46:49]
	v_mfma_f32_16x16x32_bf16 v[42:45], v[138:141], v[192:195], v[42:45]
	v_mfma_f32_16x16x32_bf16 v[42:45], v[142:145], v[196:199], v[42:45]
	v_mfma_f32_16x16x32_bf16 v[30:33], v[130:133], v[210:213], v[30:33]
	v_mfma_f32_16x16x32_bf16 v[30:33], v[134:137], v[214:217], v[30:33]
	v_mfma_f32_16x16x32_bf16 v[26:29], v[138:141], v[210:213], v[26:29]
	v_mfma_f32_16x16x32_bf16 v[26:29], v[142:145], v[214:217], v[26:29]
	v_mfma_f32_16x16x32_bf16 v[14:17], v[130:133], v[218:221], v[14:17]
	v_mfma_f32_16x16x32_bf16 v[14:17], v[134:137], v[222:225], v[14:17]
	v_mfma_f32_16x16x32_bf16 v[10:13], v[138:141], v[218:221], v[10:13]
	v_mfma_f32_16x16x32_bf16 v[10:13], v[142:145], v[222:225], v[10:13]
	s_setprio 0
	s_setprio 1
	v_mfma_f32_16x16x32_bf16 v[54:57], v[146:149], v[184:187], v[54:57]
	v_mfma_f32_16x16x32_bf16 v[54:57], v[150:153], v[188:191], v[54:57]
	v_mfma_f32_16x16x32_bf16 v[50:53], v[176:179], v[184:187], v[50:53]
	v_mfma_f32_16x16x32_bf16 v[50:53], v[180:183], v[188:191], v[50:53]
	v_mfma_f32_16x16x32_bf16 v[38:41], v[146:149], v[192:195], v[38:41]
	v_mfma_f32_16x16x32_bf16 v[38:41], v[150:153], v[196:199], v[38:41]
	v_mfma_f32_16x16x32_bf16 v[34:37], v[176:179], v[192:195], v[34:37]
	v_mfma_f32_16x16x32_bf16 v[34:37], v[180:183], v[196:199], v[34:37]
	v_mfma_f32_16x16x32_bf16 v[22:25], v[146:149], v[210:213], v[22:25]
	v_mfma_f32_16x16x32_bf16 v[22:25], v[150:153], v[214:217], v[22:25]
	v_mfma_f32_16x16x32_bf16 v[18:21], v[176:179], v[210:213], v[18:21]
	v_mfma_f32_16x16x32_bf16 v[18:21], v[180:183], v[214:217], v[18:21]
	v_mfma_f32_16x16x32_bf16 v[6:9], v[146:149], v[218:221], v[6:9]
	v_mfma_f32_16x16x32_bf16 v[6:9], v[150:153], v[222:225], v[6:9]
	v_mfma_f32_16x16x32_bf16 v[2:5], v[176:179], v[218:221], v[2:5]
	v_mfma_f32_16x16x32_bf16 v[2:5], v[180:183], v[222:225], v[2:5]
	s_setprio 0
	s_barrier
	s_add_i32 s67, 0, 0x18000
	s_add_i32 s68, 0, 0x1c000
	v_add_u32_e32 v142, s67, v203
	v_add_u32_e32 v162, s68, v203
	ds_read_b128 v[130:133], v142
	ds_read_b128 v[134:137], v142 offset:1024
	ds_read_b128 v[138:141], v142 offset:2048
	ds_read_b128 v[142:145], v142 offset:3072
	ds_read_b128 v[146:149], v162
	ds_read_b128 v[150:153], v162 offset:1024
	ds_read_b128 v[176:179], v162 offset:2048
	ds_read_b128 v[180:183], v162 offset:3072
	s_add_u32 s46, s46, 0x400000
	s_addc_u32 s47, s47, 0
	s_mov_b32 m0, s55
	ds_read_b128 v[184:187], v208 offset:32768
	ds_read_b128 v[188:191], v208 offset:33792
	ds_read_b128 v[192:195], v208 offset:34816
	ds_read_b128 v[196:199], v208 offset:35840
	ds_read_b128 v[210:213], v208 offset:36864
	ds_read_b128 v[214:217], v208 offset:37888
	ds_read_b128 v[218:221], v208 offset:38912
	ds_read_b128 v[222:225], v208 offset:39936
	global_load_lds_dwordx4 v154, s[46:47]
	s_mov_b32 m0, s56
	s_nop 0
	global_load_lds_dwordx4 v158, s[46:47]
	s_waitcnt vmcnt(8)
	s_waitcnt lgkmcnt(0)
	s_barrier
	s_setprio 1
	s_waitcnt lgkmcnt(0)
	v_mfma_f32_16x16x32_bf16 v[126:129], v[130:133], v[184:187], v[126:129]
	v_mfma_f32_16x16x32_bf16 v[126:129], v[134:137], v[188:191], v[126:129]
	v_mfma_f32_16x16x32_bf16 v[122:125], v[138:141], v[184:187], v[122:125]
	v_mfma_f32_16x16x32_bf16 v[122:125], v[142:145], v[188:191], v[122:125]
	v_mfma_f32_16x16x32_bf16 v[110:113], v[130:133], v[192:195], v[110:113]
	v_mfma_f32_16x16x32_bf16 v[110:113], v[134:137], v[196:199], v[110:113]
	v_mfma_f32_16x16x32_bf16 v[106:109], v[138:141], v[192:195], v[106:109]
	v_mfma_f32_16x16x32_bf16 v[106:109], v[142:145], v[196:199], v[106:109]
	v_mfma_f32_16x16x32_bf16 v[94:97], v[130:133], v[210:213], v[94:97]
	v_mfma_f32_16x16x32_bf16 v[94:97], v[134:137], v[214:217], v[94:97]
	v_mfma_f32_16x16x32_bf16 v[90:93], v[138:141], v[210:213], v[90:93]
	v_mfma_f32_16x16x32_bf16 v[90:93], v[142:145], v[214:217], v[90:93]
	v_mfma_f32_16x16x32_bf16 v[78:81], v[130:133], v[218:221], v[78:81]
	v_mfma_f32_16x16x32_bf16 v[78:81], v[134:137], v[222:225], v[78:81]
	v_mfma_f32_16x16x32_bf16 v[74:77], v[138:141], v[218:221], v[74:77]
	v_mfma_f32_16x16x32_bf16 v[74:77], v[142:145], v[222:225], v[74:77]
	s_setprio 0
	s_setprio 1
	v_mfma_f32_16x16x32_bf16 v[118:121], v[146:149], v[184:187], v[118:121]
	v_mfma_f32_16x16x32_bf16 v[118:121], v[150:153], v[188:191], v[118:121]
	v_mfma_f32_16x16x32_bf16 v[114:117], v[176:179], v[184:187], v[114:117]
	v_mfma_f32_16x16x32_bf16 v[114:117], v[180:183], v[188:191], v[114:117]
	v_mfma_f32_16x16x32_bf16 v[102:105], v[146:149], v[192:195], v[102:105]
	v_mfma_f32_16x16x32_bf16 v[102:105], v[150:153], v[196:199], v[102:105]
	v_mfma_f32_16x16x32_bf16 v[98:101], v[176:179], v[192:195], v[98:101]
	v_mfma_f32_16x16x32_bf16 v[98:101], v[180:183], v[196:199], v[98:101]
	v_mfma_f32_16x16x32_bf16 v[86:89], v[146:149], v[210:213], v[86:89]
	v_mfma_f32_16x16x32_bf16 v[86:89], v[150:153], v[214:217], v[86:89]
	v_mfma_f32_16x16x32_bf16 v[82:85], v[176:179], v[210:213], v[82:85]
	v_mfma_f32_16x16x32_bf16 v[82:85], v[180:183], v[214:217], v[82:85]
	v_mfma_f32_16x16x32_bf16 v[70:73], v[146:149], v[218:221], v[70:73]
	v_mfma_f32_16x16x32_bf16 v[70:73], v[150:153], v[222:225], v[70:73]
	v_mfma_f32_16x16x32_bf16 v[66:69], v[176:179], v[218:221], v[66:69]
	v_mfma_f32_16x16x32_bf16 v[66:69], v[180:183], v[222:225], v[66:69]
	s_setprio 0
	s_barrier
	s_add_u32 s46, s44, 0x4000
	s_addc_u32 s47, s45, 0
	s_add_i32 s67, s67, s52
	s_mov_b32 m0, s67
	ds_read_b128 v[184:187], v208 offset:49152
	ds_read_b128 v[188:191], v208 offset:50176
	ds_read_b128 v[192:195], v208 offset:51200
	ds_read_b128 v[196:199], v208 offset:52224
	ds_read_b128 v[210:213], v208 offset:53248
	ds_read_b128 v[214:217], v208 offset:54272
	ds_read_b128 v[218:221], v208 offset:55296
	ds_read_b128 v[222:225], v208 offset:56320
	global_load_lds_dwordx4 v156, s[46:47]
	s_add_i32 m0, s67, 0x2000
	s_add_u32 s44, s44, 0x404000
	s_addc_u32 s45, s45, 0
	global_load_lds_dwordx4 v160, s[46:47]
	s_add_i32 s46, s68, s52
	s_mov_b32 m0, s46
	s_nop 0
	global_load_lds_dwordx4 v156, s[44:45]
	s_add_i32 m0, s46, 0x2000
	s_nop 0
	global_load_lds_dwordx4 v160, s[44:45]
	s_mov_b32 m0, s60
	s_nop 0
	global_load_lds_dwordx4 v154, s[42:43]
	s_mov_b32 m0, s61
	s_nop 0
	global_load_lds_dwordx4 v158, s[42:43]
	s_waitcnt vmcnt(8)
	s_waitcnt lgkmcnt(0)
	s_barrier
	s_setprio 1
	s_waitcnt lgkmcnt(0)
	v_mfma_f32_16x16x32_bf16 v[62:65], v[130:133], v[184:187], v[62:65]
	v_mfma_f32_16x16x32_bf16 v[62:65], v[134:137], v[188:191], v[62:65]
	v_mfma_f32_16x16x32_bf16 v[58:61], v[138:141], v[184:187], v[58:61]
	v_mfma_f32_16x16x32_bf16 v[58:61], v[142:145], v[188:191], v[58:61]
	v_mfma_f32_16x16x32_bf16 v[46:49], v[130:133], v[192:195], v[46:49]
	v_mfma_f32_16x16x32_bf16 v[46:49], v[134:137], v[196:199], v[46:49]
	v_mfma_f32_16x16x32_bf16 v[42:45], v[138:141], v[192:195], v[42:45]
	v_mfma_f32_16x16x32_bf16 v[42:45], v[142:145], v[196:199], v[42:45]
	v_mfma_f32_16x16x32_bf16 v[30:33], v[130:133], v[210:213], v[30:33]
	v_mfma_f32_16x16x32_bf16 v[30:33], v[134:137], v[214:217], v[30:33]
	v_mfma_f32_16x16x32_bf16 v[26:29], v[138:141], v[210:213], v[26:29]
	v_mfma_f32_16x16x32_bf16 v[26:29], v[142:145], v[214:217], v[26:29]
	v_mfma_f32_16x16x32_bf16 v[14:17], v[130:133], v[218:221], v[14:17]
	v_mfma_f32_16x16x32_bf16 v[14:17], v[134:137], v[222:225], v[14:17]
	v_mfma_f32_16x16x32_bf16 v[10:13], v[138:141], v[218:221], v[10:13]
	v_mfma_f32_16x16x32_bf16 v[10:13], v[142:145], v[222:225], v[10:13]
	s_setprio 0
	s_setprio 1
	v_mfma_f32_16x16x32_bf16 v[54:57], v[146:149], v[184:187], v[54:57]
	v_mfma_f32_16x16x32_bf16 v[54:57], v[150:153], v[188:191], v[54:57]
	v_mfma_f32_16x16x32_bf16 v[50:53], v[176:179], v[184:187], v[50:53]
	v_mfma_f32_16x16x32_bf16 v[50:53], v[180:183], v[188:191], v[50:53]
	v_mfma_f32_16x16x32_bf16 v[38:41], v[146:149], v[192:195], v[38:41]
	v_mfma_f32_16x16x32_bf16 v[38:41], v[150:153], v[196:199], v[38:41]
	v_mfma_f32_16x16x32_bf16 v[34:37], v[176:179], v[192:195], v[34:37]
	v_mfma_f32_16x16x32_bf16 v[34:37], v[180:183], v[196:199], v[34:37]
	v_mfma_f32_16x16x32_bf16 v[22:25], v[146:149], v[210:213], v[22:25]
	v_mfma_f32_16x16x32_bf16 v[22:25], v[150:153], v[214:217], v[22:25]
	v_mfma_f32_16x16x32_bf16 v[18:21], v[176:179], v[210:213], v[18:21]
	v_mfma_f32_16x16x32_bf16 v[18:21], v[180:183], v[214:217], v[18:21]
	v_mfma_f32_16x16x32_bf16 v[6:9], v[146:149], v[218:221], v[6:9]
	v_mfma_f32_16x16x32_bf16 v[6:9], v[150:153], v[222:225], v[6:9]
	v_mfma_f32_16x16x32_bf16 v[2:5], v[176:179], v[218:221], v[2:5]
	v_mfma_f32_16x16x32_bf16 v[2:5], v[180:183], v[222:225], v[2:5]
	s_setprio 0
	s_barrier
	s_add_i32 s66, s66, 2
	s_add_u32 s40, s40, 0x8000
	s_addc_u32 s41, s41, 0
	s_add_u32 s39, s39, 0x8000
	s_addc_u32 s65, s65, 0
	s_cmpk_gt_u32 s66, 0xfd
	s_cbranch_scc0 .LBB0_1292
	s_and_b64 vcc, exec, s[24:25]
	s_cbranch_vccz .LBB0_1295
	s_barrier

.LBB0_1387:
	ds_read_b128 v[62:65], v189
	ds_read_b128 v[66:69], v189 offset:1024
	ds_read_b128 v[74:77], v189 offset:2048
	ds_read_b128 v[78:81], v189 offset:3072
	ds_read_b128 v[146:149], v195
	ds_read_b128 v[150:153], v195 offset:1024
	ds_read_b128 v[154:157], v195 offset:2048
	ds_read_b128 v[158:161], v195 offset:3072
	s_add_u32 s34, s30, 0xfff04000
	s_addc_u32 s35, s31, -1
	s_cmp_eq_u32 s54, 60
	s_cselect_b32 s38, s27, s34
	s_cselect_b32 s39, s21, s35
	s_cselect_b32 s36, s29, s52
	s_cselect_b32 s37, s19, s53
	s_add_u32 s34, s38, 0x4000
	s_addc_u32 s35, s39, 0
	s_add_i32 m0, s40, 0xc000
	ds_read_b128 v[190:193], v197
	ds_read_b128 v[198:201], v197 offset:1024
	ds_read_b128 v[202:205], v197 offset:2048
	ds_read_b128 v[206:209], v197 offset:3072
	ds_read_b128 v[210:213], v197 offset:4096
	ds_read_b128 v[214:217], v197 offset:5120
	ds_read_b128 v[218:221], v197 offset:6144
	ds_read_b128 v[222:225], v197 offset:7168
	global_load_lds_dwordx4 v172, s[30:31]
	s_add_i32 m0, s40, 0xe000
	s_nop 0
	global_load_lds_dwordx4 v174, s[30:31]
	s_waitcnt vmcnt(8)
	s_waitcnt lgkmcnt(0)
	s_barrier
	s_setprio 1
	s_waitcnt lgkmcnt(0)
	v_mfma_f32_16x16x32_bf16 v[142:145], v[62:65], v[190:193], v[142:145]
	v_mfma_f32_16x16x32_bf16 v[142:145], v[66:69], v[198:201], v[142:145]
	v_mfma_f32_16x16x32_bf16 v[138:141], v[74:77], v[190:193], v[138:141]
	v_mfma_f32_16x16x32_bf16 v[138:141], v[78:81], v[198:201], v[138:141]
	v_mfma_f32_16x16x32_bf16 v[126:129], v[62:65], v[202:205], v[126:129]
	v_mfma_f32_16x16x32_bf16 v[126:129], v[66:69], v[206:209], v[126:129]
	v_mfma_f32_16x16x32_bf16 v[122:125], v[74:77], v[202:205], v[122:125]
	v_mfma_f32_16x16x32_bf16 v[122:125], v[78:81], v[206:209], v[122:125]
	v_mfma_f32_16x16x32_bf16 v[110:113], v[62:65], v[210:213], v[110:113]
	v_mfma_f32_16x16x32_bf16 v[110:113], v[66:69], v[214:217], v[110:113]
	v_mfma_f32_16x16x32_bf16 v[106:109], v[74:77], v[210:213], v[106:109]
	v_mfma_f32_16x16x32_bf16 v[106:109], v[78:81], v[214:217], v[106:109]
	v_mfma_f32_16x16x32_bf16 v[94:97], v[62:65], v[218:221], v[94:97]
	v_mfma_f32_16x16x32_bf16 v[94:97], v[66:69], v[222:225], v[94:97]
	v_mfma_f32_16x16x32_bf16 v[90:93], v[74:77], v[218:221], v[90:93]
	v_mfma_f32_16x16x32_bf16 v[90:93], v[78:81], v[222:225], v[90:93]
	s_setprio 0
	s_setprio 1
	v_mfma_f32_16x16x32_bf16 v[134:137], v[146:149], v[190:193], v[134:137]
	v_mfma_f32_16x16x32_bf16 v[134:137], v[150:153], v[198:201], v[134:137]
	v_mfma_f32_16x16x32_bf16 v[130:133], v[154:157], v[190:193], v[130:133]
	v_mfma_f32_16x16x32_bf16 v[130:133], v[158:161], v[198:201], v[130:133]
	v_mfma_f32_16x16x32_bf16 v[118:121], v[146:149], v[202:205], v[118:121]
	v_mfma_f32_16x16x32_bf16 v[118:121], v[150:153], v[206:209], v[118:121]
	v_mfma_f32_16x16x32_bf16 v[114:117], v[154:157], v[202:205], v[114:117]
	v_mfma_f32_16x16x32_bf16 v[114:117], v[158:161], v[206:209], v[114:117]
	v_mfma_f32_16x16x32_bf16 v[102:105], v[146:149], v[210:213], v[102:105]
	v_mfma_f32_16x16x32_bf16 v[102:105], v[150:153], v[214:217], v[102:105]
	v_mfma_f32_16x16x32_bf16 v[98:101], v[154:157], v[210:213], v[98:101]
	v_mfma_f32_16x16x32_bf16 v[98:101], v[158:161], v[214:217], v[98:101]
	v_mfma_f32_16x16x32_bf16 v[86:89], v[146:149], v[218:221], v[86:89]
	v_mfma_f32_16x16x32_bf16 v[86:89], v[150:153], v[222:225], v[86:89]
	v_mfma_f32_16x16x32_bf16 v[82:85], v[154:157], v[218:221], v[82:85]
	v_mfma_f32_16x16x32_bf16 v[82:85], v[158:161], v[222:225], v[82:85]
	s_setprio 0
	s_barrier
	s_add_i32 s55, s50, s33
	s_mov_b32 m0, s55
	ds_read_b128 v[190:193], v197 offset:16384
	ds_read_b128 v[198:201], v197 offset:17408
	ds_read_b128 v[202:205], v197 offset:18432
	ds_read_b128 v[206:209], v197 offset:19456
	ds_read_b128 v[210:213], v197 offset:20480
	ds_read_b128 v[214:217], v197 offset:21504
	ds_read_b128 v[218:221], v197 offset:22528
	ds_read_b128 v[222:225], v197 offset:23552
	global_load_lds_dwordx4 v166, s[36:37]
	s_add_i32 m0, s55, 0x2000
	s_add_u32 s56, s36, 0x100000
	s_addc_u32 s57, s37, 0
	s_add_i32 s55, s51, s33
	global_load_lds_dwordx4 v162, s[36:37]
	s_mov_b32 m0, s55
	s_nop 0
	global_load_lds_dwordx4 v166, s[56:57]
	s_add_i32 m0, s55, 0x2000
	s_nop 0
	global_load_lds_dwordx4 v162, s[56:57]
	s_mov_b32 m0, s40
	s_nop 0
	global_load_lds_dwordx4 v168, s[38:39]
	s_mov_b32 m0, s41
	s_nop 0
	global_load_lds_dwordx4 v164, s[38:39]
	s_waitcnt vmcnt(8)
	s_waitcnt lgkmcnt(0)
	s_barrier
	s_setprio 1
	s_waitcnt lgkmcnt(0)
	v_mfma_f32_16x16x32_bf16 v[70:73], v[62:65], v[190:193], v[70:73]
	v_mfma_f32_16x16x32_bf16 v[70:73], v[66:69], v[198:201], v[70:73]
	v_mfma_f32_16x16x32_bf16 v[58:61], v[74:77], v[190:193], v[58:61]
	v_mfma_f32_16x16x32_bf16 v[58:61], v[78:81], v[198:201], v[58:61]
	v_mfma_f32_16x16x32_bf16 v[46:49], v[62:65], v[202:205], v[46:49]
	v_mfma_f32_16x16x32_bf16 v[46:49], v[66:69], v[206:209], v[46:49]
	v_mfma_f32_16x16x32_bf16 v[42:45], v[74:77], v[202:205], v[42:45]
	v_mfma_f32_16x16x32_bf16 v[42:45], v[78:81], v[206:209], v[42:45]
	v_mfma_f32_16x16x32_bf16 v[30:33], v[62:65], v[210:213], v[30:33]
	v_mfma_f32_16x16x32_bf16 v[30:33], v[66:69], v[214:217], v[30:33]
	v_mfma_f32_16x16x32_bf16 v[26:29], v[74:77], v[210:213], v[26:29]
	v_mfma_f32_16x16x32_bf16 v[26:29], v[78:81], v[214:217], v[26:29]
	v_mfma_f32_16x16x32_bf16 v[14:17], v[62:65], v[218:221], v[14:17]
	v_mfma_f32_16x16x32_bf16 v[14:17], v[66:69], v[222:225], v[14:17]
	v_mfma_f32_16x16x32_bf16 v[10:13], v[74:77], v[218:221], v[10:13]
	v_mfma_f32_16x16x32_bf16 v[10:13], v[78:81], v[222:225], v[10:13]
	s_setprio 0
	s_setprio 1
	v_mfma_f32_16x16x32_bf16 v[54:57], v[146:149], v[190:193], v[54:57]
	v_mfma_f32_16x16x32_bf16 v[54:57], v[150:153], v[198:201], v[54:57]
	v_mfma_f32_16x16x32_bf16 v[50:53], v[154:157], v[190:193], v[50:53]
	v_mfma_f32_16x16x32_bf16 v[50:53], v[158:161], v[198:201], v[50:53]
	v_mfma_f32_16x16x32_bf16 v[38:41], v[146:149], v[202:205], v[38:41]
	v_mfma_f32_16x16x32_bf16 v[38:41], v[150:153], v[206:209], v[38:41]
	v_mfma_f32_16x16x32_bf16 v[34:37], v[154:157], v[202:205], v[34:37]
	v_mfma_f32_16x16x32_bf16 v[34:37], v[158:161], v[206:209], v[34:37]
	v_mfma_f32_16x16x32_bf16 v[22:25], v[146:149], v[210:213], v[22:25]
	v_mfma_f32_16x16x32_bf16 v[22:25], v[150:153], v[214:217], v[22:25]
	v_mfma_f32_16x16x32_bf16 v[18:21], v[154:157], v[210:213], v[18:21]
	v_mfma_f32_16x16x32_bf16 v[18:21], v[158:161], v[214:217], v[18:21]
	v_mfma_f32_16x16x32_bf16 v[6:9], v[146:149], v[218:221], v[6:9]
	v_mfma_f32_16x16x32_bf16 v[6:9], v[150:153], v[222:225], v[6:9]
	v_mfma_f32_16x16x32_bf16 v[2:5], v[154:157], v[218:221], v[2:5]
	v_mfma_f32_16x16x32_bf16 v[2:5], v[158:161], v[222:225], v[2:5]
	s_setprio 0
	s_barrier
	s_add_i32 s55, 0, 0x18000
	s_add_i32 s56, 0, 0x1c000
	v_add_u32_e32 v78, s55, v187
	v_add_u32_e32 v158, s56, v187
	ds_read_b128 v[62:65], v78
	ds_read_b128 v[66:69], v78 offset:1024
	ds_read_b128 v[74:77], v78 offset:2048
	ds_read_b128 v[78:81], v78 offset:3072
	ds_read_b128 v[146:149], v158
	ds_read_b128 v[150:153], v158 offset:1024
	ds_read_b128 v[154:157], v158 offset:2048
	ds_read_b128 v[158:161], v158 offset:3072
	s_add_u32 s38, s38, 0x100000
	s_addc_u32 s39, s39, 0
	s_mov_b32 m0, s42
	ds_read_b128 v[190:193], v197 offset:32768
	ds_read_b128 v[198:201], v197 offset:33792
	ds_read_b128 v[202:205], v197 offset:34816
	ds_read_b128 v[206:209], v197 offset:35840
	ds_read_b128 v[210:213], v197 offset:36864
	ds_read_b128 v[214:217], v197 offset:37888
	ds_read_b128 v[218:221], v197 offset:38912
	ds_read_b128 v[222:225], v197 offset:39936
	global_load_lds_dwordx4 v168, s[38:39]
	s_mov_b32 m0, s43
	s_nop 0
	global_load_lds_dwordx4 v164, s[38:39]
	s_waitcnt vmcnt(8)
	s_waitcnt lgkmcnt(0)
	s_barrier
	s_setprio 1
	s_waitcnt lgkmcnt(0)
	v_mfma_f32_16x16x32_bf16 v[142:145], v[62:65], v[190:193], v[142:145]
	v_mfma_f32_16x16x32_bf16 v[142:145], v[66:69], v[198:201], v[142:145]
	v_mfma_f32_16x16x32_bf16 v[138:141], v[74:77], v[190:193], v[138:141]
	v_mfma_f32_16x16x32_bf16 v[138:141], v[78:81], v[198:201], v[138:141]
	v_mfma_f32_16x16x32_bf16 v[126:129], v[62:65], v[202:205], v[126:129]
	v_mfma_f32_16x16x32_bf16 v[126:129], v[66:69], v[206:209], v[126:129]
	v_mfma_f32_16x16x32_bf16 v[122:125], v[74:77], v[202:205], v[122:125]
	v_mfma_f32_16x16x32_bf16 v[122:125], v[78:81], v[206:209], v[122:125]
	v_mfma_f32_16x16x32_bf16 v[110:113], v[62:65], v[210:213], v[110:113]
	v_mfma_f32_16x16x32_bf16 v[110:113], v[66:69], v[214:217], v[110:113]
	v_mfma_f32_16x16x32_bf16 v[106:109], v[74:77], v[210:213], v[106:109]
	v_mfma_f32_16x16x32_bf16 v[106:109], v[78:81], v[214:217], v[106:109]
	v_mfma_f32_16x16x32_bf16 v[94:97], v[62:65], v[218:221], v[94:97]
	v_mfma_f32_16x16x32_bf16 v[94:97], v[66:69], v[222:225], v[94:97]
	v_mfma_f32_16x16x32_bf16 v[90:93], v[74:77], v[218:221], v[90:93]
	v_mfma_f32_16x16x32_bf16 v[90:93], v[78:81], v[222:225], v[90:93]
	s_setprio 0
	s_setprio 1
	v_mfma_f32_16x16x32_bf16 v[134:137], v[146:149], v[190:193], v[134:137]
	v_mfma_f32_16x16x32_bf16 v[134:137], v[150:153], v[198:201], v[134:137]
	v_mfma_f32_16x16x32_bf16 v[130:133], v[154:157], v[190:193], v[130:133]
	v_mfma_f32_16x16x32_bf16 v[130:133], v[158:161], v[198:201], v[130:133]
	v_mfma_f32_16x16x32_bf16 v[118:121], v[146:149], v[202:205], v[118:121]
	v_mfma_f32_16x16x32_bf16 v[118:121], v[150:153], v[206:209], v[118:121]
	v_mfma_f32_16x16x32_bf16 v[114:117], v[154:157], v[202:205], v[114:117]
	v_mfma_f32_16x16x32_bf16 v[114:117], v[158:161], v[206:209], v[114:117]
	v_mfma_f32_16x16x32_bf16 v[102:105], v[146:149], v[210:213], v[102:105]
	v_mfma_f32_16x16x32_bf16 v[102:105], v[150:153], v[214:217], v[102:105]
	v_mfma_f32_16x16x32_bf16 v[98:101], v[154:157], v[210:213], v[98:101]
	v_mfma_f32_16x16x32_bf16 v[98:101], v[158:161], v[214:217], v[98:101]
	v_mfma_f32_16x16x32_bf16 v[86:89], v[146:149], v[218:221], v[86:89]
	v_mfma_f32_16x16x32_bf16 v[86:89], v[150:153], v[222:225], v[86:89]
	v_mfma_f32_16x16x32_bf16 v[82:85], v[154:157], v[218:221], v[82:85]
	v_mfma_f32_16x16x32_bf16 v[82:85], v[158:161], v[222:225], v[82:85]
	s_setprio 0
	s_barrier
	s_add_u32 s38, s36, 0x4000
	s_addc_u32 s39, s37, 0
	s_add_i32 s55, s55, s33
	s_mov_b32 m0, s55
	ds_read_b128 v[190:193], v197 offset:49152
	ds_read_b128 v[198:201], v197 offset:50176
	ds_read_b128 v[202:205], v197 offset:51200
	ds_read_b128 v[206:209], v197 offset:52224
	ds_read_b128 v[210:213], v197 offset:53248
	ds_read_b128 v[214:217], v197 offset:54272
	ds_read_b128 v[218:221], v197 offset:55296
	ds_read_b128 v[222:225], v197 offset:56320
	global_load_lds_dwordx4 v166, s[38:39]
	s_add_i32 m0, s55, 0x2000
	s_add_u32 s36, s36, 0x104000
	s_addc_u32 s37, s37, 0
	global_load_lds_dwordx4 v162, s[38:39]
	s_add_i32 s38, s56, s33
	s_mov_b32 m0, s38
	s_nop 0
	global_load_lds_dwordx4 v166, s[36:37]
	s_add_i32 m0, s38, 0x2000
	s_nop 0
	global_load_lds_dwordx4 v162, s[36:37]
	s_mov_b32 m0, s46
	s_nop 0
	global_load_lds_dwordx4 v168, s[34:35]
	s_mov_b32 m0, s47
	s_nop 0
	global_load_lds_dwordx4 v164, s[34:35]
	s_waitcnt vmcnt(8)
	s_waitcnt lgkmcnt(0)
	s_barrier
	s_setprio 1
	s_waitcnt lgkmcnt(0)
	v_mfma_f32_16x16x32_bf16 v[70:73], v[62:65], v[190:193], v[70:73]
	v_mfma_f32_16x16x32_bf16 v[70:73], v[66:69], v[198:201], v[70:73]
	v_mfma_f32_16x16x32_bf16 v[58:61], v[74:77], v[190:193], v[58:61]
	v_mfma_f32_16x16x32_bf16 v[58:61], v[78:81], v[198:201], v[58:61]
	v_mfma_f32_16x16x32_bf16 v[46:49], v[62:65], v[202:205], v[46:49]
	v_mfma_f32_16x16x32_bf16 v[46:49], v[66:69], v[206:209], v[46:49]
	v_mfma_f32_16x16x32_bf16 v[42:45], v[74:77], v[202:205], v[42:45]
	v_mfma_f32_16x16x32_bf16 v[42:45], v[78:81], v[206:209], v[42:45]
	v_mfma_f32_16x16x32_bf16 v[30:33], v[62:65], v[210:213], v[30:33]
	v_mfma_f32_16x16x32_bf16 v[30:33], v[66:69], v[214:217], v[30:33]
	v_mfma_f32_16x16x32_bf16 v[26:29], v[74:77], v[210:213], v[26:29]
	v_mfma_f32_16x16x32_bf16 v[26:29], v[78:81], v[214:217], v[26:29]
	v_mfma_f32_16x16x32_bf16 v[14:17], v[62:65], v[218:221], v[14:17]
	v_mfma_f32_16x16x32_bf16 v[14:17], v[66:69], v[222:225], v[14:17]
	v_mfma_f32_16x16x32_bf16 v[10:13], v[74:77], v[218:221], v[10:13]
	v_mfma_f32_16x16x32_bf16 v[10:13], v[78:81], v[222:225], v[10:13]
	s_setprio 0
	s_setprio 1
	v_mfma_f32_16x16x32_bf16 v[54:57], v[146:149], v[190:193], v[54:57]
	v_mfma_f32_16x16x32_bf16 v[54:57], v[150:153], v[198:201], v[54:57]
	v_mfma_f32_16x16x32_bf16 v[50:53], v[154:157], v[190:193], v[50:53]
	v_mfma_f32_16x16x32_bf16 v[50:53], v[158:161], v[198:201], v[50:53]
	v_mfma_f32_16x16x32_bf16 v[38:41], v[146:149], v[202:205], v[38:41]
	v_mfma_f32_16x16x32_bf16 v[38:41], v[150:153], v[206:209], v[38:41]
	v_mfma_f32_16x16x32_bf16 v[34:37], v[154:157], v[202:205], v[34:37]
	v_mfma_f32_16x16x32_bf16 v[34:37], v[158:161], v[206:209], v[34:37]
	v_mfma_f32_16x16x32_bf16 v[22:25], v[146:149], v[210:213], v[22:25]
	v_mfma_f32_16x16x32_bf16 v[22:25], v[150:153], v[214:217], v[22:25]
	v_mfma_f32_16x16x32_bf16 v[18:21], v[154:157], v[210:213], v[18:21]
	v_mfma_f32_16x16x32_bf16 v[18:21], v[158:161], v[214:217], v[18:21]
	v_mfma_f32_16x16x32_bf16 v[6:9], v[146:149], v[218:221], v[6:9]
	v_mfma_f32_16x16x32_bf16 v[6:9], v[150:153], v[222:225], v[6:9]
	v_mfma_f32_16x16x32_bf16 v[2:5], v[154:157], v[218:221], v[2:5]
	v_mfma_f32_16x16x32_bf16 v[2:5], v[158:161], v[222:225], v[2:5]
	s_setprio 0
	s_barrier
	s_add_i32 s54, s54, 2
	s_add_u32 s30, s30, 0x8000
	s_addc_u32 s31, s31, 0
	s_add_u32 s52, s52, 0x8000
	s_addc_u32 s53, s53, 0
	s_cmp_gt_u32 s54, 61
	s_cbranch_scc0 .LBB0_1387
	s_and_b64 vcc, exec, s[12:13]
	s_cbranch_vccz .LBB0_1390
	s_barrier
